# attention: QK^T K-fragment reads double-buffered with the softmax-finish VALU spread over the MFMAs; K tile swizzle widened to 16 rows (conflict-free ds_read_b128)
# speedup vs baseline: 1.0020x; 1.0020x over previous
.LBB0_958:
	v_lshlrev_b32_e32 v177, 1, v144
	s_movk_i32 s0, 0xf0
	s_waitcnt vmcnt(0)
	v_lshlrev_b32_e32 v0, 8, v175
	v_bitop3_b32 v1, v177, v145, s0 bitop3:0x78
	v_add3_u32 v3, 0, v0, v1
	s_andn2_b64 vcc, exec, s[6:7]
	s_waitcnt vmcnt(2)
	ds_write_b128 v3, v[68:71] offset:32768
	s_waitcnt vmcnt(0)
	ds_write_b128 v3, v[72:75] offset:40960
	s_cbranch_vccnz .LBB0_960
	v_lshl_add_u32 v3, v176, 2, 0
	v_add_u32_e32 v3, 0x10800, v3
	ds_write_b32 v3, v179
.LBB0_960:
	s_add_u32 s62, s4, 0x2fa04000
	v_and_b32_e32 v4, 0xfffff0, v175
	v_lshlrev_b32_e32 v5, 1, v175
	s_addc_u32 s63, s5, 0
	v_and_or_b32 v4, v5, 8, v4
	s_add_u32 s64, s4, 0x2fa05000
	v_lshrrev_b32_e32 v4, 1, v4
	v_lshrrev_b32_e32 v6, 5, v144
	s_addc_u32 s65, s5, 0
	v_lshrrev_b32_e32 v5, 1, v175
	v_or_b32_e32 v4, v4, v6
	v_bfe_u32 v6, v145, 4, 2
	s_add_u32 s66, s4, 0x2fa02000
	v_and_or_b32 v5, v5, 4, v6
	v_and_b32_e32 v6, 48, v177
	s_addc_u32 s67, s5, 0
	v_lshl_or_b32 v5, v5, 6, v6
	s_add_u32 s68, s4, 0x2fa03000
	v_lshl_or_b32 v5, v4, 9, v5
	v_lshlrev_b32_e32 v4, 4, v176
	s_addc_u32 s69, s5, 0
	v_or_b32_e32 v1, v1, v0
	v_lshlrev_b32_e32 v0, 3, v176
	v_and_b32_e32 v4, 0xc0, v4
	v_lshlrev_b32_e32 v6, 1, v176
	v_and_or_b32 v4, v0, 24, v4
	v_and_b32_e32 v6, 32, v6
	v_and_b32_e32 v0, 0x100, v0
	s_cmp_lg_u32 0, -1
	v_lshrrev_b32_e32 v3, 5, v176
	v_or3_b32 v0, v4, v6, v0
	s_cselect_b32 s0, 0, 0
	v_add_u32_e32 v180, s0, v0
	v_lshlrev_b32_e32 v182, 4, v3
	v_lshlrev_b32_e32 v0, 4, v174
	v_and_b32_e32 v0, 0xf0, v0
	v_or_b32_e32 v4, 32, v182
	v_xad_u32 v10, v4, v0, 0
	v_or_b32_e32 v4, 64, v182
	v_xad_u32 v11, v4, v0, 0
	v_or_b32_e32 v4, 0x60, v182
	v_lshlrev_b32_e32 v178, 2, v3
	v_xad_u32 v9, v182, v0, 0
	v_xad_u32 v12, v4, v0, 0
	s_add_i32 s0, 0, 0x10800
	v_and_b32_e32 v0, 1, v2
	v_mul_u32_u24_e32 v184, 0x440, v3
	v_lshrrev_b32_e32 v3, 4, v176
	v_lshl_add_u32 v183, v176, 2, s0
	v_cmp_eq_u32_e64 s[6:7], 0, v0
	s_movk_i32 s0, 0x1800
	v_mul_u32_u24_e32 v0, 0x1800, v3
	v_mov_b32_e32 v4, 0x1e000
	v_mov_b32_e32 v6, 0x24000
	v_mov_b32_e32 v8, 0x2a000
	v_lshlrev_b32_e32 v7, 8, v174
	v_mul_u32_u24_e32 v185, 0x110, v3
	v_or_b32_e32 v2, 0x18000, v0
	v_mad_u32_u24 v4, v3, s0, v4
	v_mad_u32_u24 v6, v3, s0, v6
	v_mad_u32_u24 v8, v3, s0, v8
	v_sub_u32_e32 v3, v174, v178
	s_mov_b32 s21, 0
	v_or_b32_e32 v181, 0x60000, v144
	v_cmp_gt_u32_e64 s[4:5], 32, v176
	v_mov_b32_e32 v147, 0
	s_mov_b32 s70, 0x18000
	s_mov_b32 s71, 0x24000
	v_add_u32_e32 v186, 0xbfffff45, v3
	s_movk_i32 s75, 0x6000
	s_movk_i32 s76, 0x3000
	s_mov_b32 s77, 0x41000000
	s_mov_b32 s30, 0x3e0293ee
	s_brev_b32 s78, -3
	v_lshlrev_b32_e32 v146, 1, v144
	v_lshlrev_b32_e32 v148, 1, v0
	s_mov_b32 s79, 0xc000
	v_lshlrev_b32_e32 v150, 1, v2
	v_lshlrev_b32_e32 v152, 1, v4
	v_lshlrev_b32_e32 v154, 1, v6
	v_lshlrev_b32_e32 v156, 1, v8
	v_add_u32_e32 v187, 0, v5
	v_mov_b32_e32 v188, 0x3fd0
	v_add_u32_e32 v189, v9, v7
	v_xor_b32_e32 v248, 0x80, v189
	v_add_u32_e32 v190, v10, v7
	v_xor_b32_e32 v249, 0x80, v190
	v_add_u32_e32 v191, v11, v7
	v_xor_b32_e32 v250, 0x80, v191
	v_add_u32_e32 v192, v12, v7
	v_xor_b32_e32 v251, 0x80, v192
	v_mov_b32_e32 v193, 0xff800000
	v_add_u32_e32 v194, 0, v1
	s_waitcnt lgkmcnt(0)
	s_barrier
	s_branch .LBB0_963

.LBB0_977:
	v_add_u32_e32 v157, 0, v182
	v_add_u32_e32 v197, 0x10800, v157
	ds_read_b128 v[0:3], v189 offset:32768
	ds_read_b128 v[16:19], v197
	ds_read_b128 v[20:23], v197 offset:32
	ds_read_b128 v[24:27], v197 offset:64
	ds_read_b128 v[28:31], v197 offset:96
	ds_read_b128 v[32:35], v189 offset:40960
	ds_read_b128 v[36:39], v248 offset:32768
	s_cmp_eq_u32 s84, 0
	s_waitcnt vmcnt(15) lgkmcnt(2)
	v_mfma_f32_32x32x16_bf16 v[16:31], v[0:3], v[96:99], v[16:31]
	ds_read_b128 v[0:3], v197 offset:128
	ds_read_b128 v[4:7], v197 offset:160
	ds_read_b128 v[8:11], v197 offset:192
	ds_read_b128 v[12:15], v197 offset:224
	ds_read_b128 v[40:43], v248 offset:40960
	s_cselect_b64 vcc, -1, 0
	s_waitcnt lgkmcnt(1)
	v_mfma_f32_32x32x16_bf16 v[0:15], v[32:35], v[96:99], v[0:15]
	ds_read_b128 v[32:35], v190 offset:32768
	ds_read_b128 v[44:47], v249 offset:32768
	s_waitcnt vmcnt(14) lgkmcnt(1)
	v_mfma_f32_32x32x16_bf16 v[16:31], v[32:35], v[100:103], v[16:31]
	ds_read_b128 v[32:35], v190 offset:40960
	ds_read_b128 v[48:51], v249 offset:40960
	s_waitcnt lgkmcnt(1)
	v_mfma_f32_32x32x16_bf16 v[0:15], v[32:35], v[100:103], v[0:15]
	ds_read_b128 v[32:35], v191 offset:32768
	ds_read_b128 v[52:55], v250 offset:32768
	s_waitcnt vmcnt(13) lgkmcnt(1)
	v_mfma_f32_32x32x16_bf16 v[16:31], v[32:35], v[104:107], v[16:31]
	ds_read_b128 v[32:35], v191 offset:40960
	ds_read_b128 v[56:59], v250 offset:40960
	s_waitcnt lgkmcnt(1)
	v_mfma_f32_32x32x16_bf16 v[0:15], v[32:35], v[104:107], v[0:15]
	ds_read_b128 v[32:35], v192 offset:32768
	ds_read_b128 v[60:63], v251 offset:32768
	s_waitcnt vmcnt(12) lgkmcnt(1)
	v_mfma_f32_32x32x16_bf16 v[16:31], v[32:35], v[108:111], v[16:31]
	ds_read_b128 v[32:35], v192 offset:40960
	ds_read_b128 v[80:83], v251 offset:40960
	s_waitcnt vmcnt(11)
	v_mfma_f32_32x32x16_bf16 v[16:31], v[36:39], v[112:115], v[16:31]
	s_waitcnt lgkmcnt(1)
	v_mfma_f32_32x32x16_bf16 v[0:15], v[32:35], v[108:111], v[0:15]
	s_waitcnt vmcnt(10)
	v_mfma_f32_32x32x16_bf16 v[16:31], v[44:47], v[116:119], v[16:31]
	v_mfma_f32_32x32x16_bf16 v[0:15], v[40:43], v[112:115], v[0:15]
	s_waitcnt vmcnt(9)
	v_mfma_f32_32x32x16_bf16 v[16:31], v[52:55], v[120:123], v[16:31]
	v_mfma_f32_32x32x16_bf16 v[0:15], v[48:51], v[116:119], v[0:15]
	s_waitcnt vmcnt(8)
	v_mfma_f32_32x32x16_bf16 v[16:31], v[60:63], v[124:127], v[16:31]
	v_mfma_f32_32x32x16_bf16 v[0:15], v[56:59], v[120:123], v[0:15]
	s_nop 10
	v_cndmask_b32_e32 v17, v17, v193, vcc
	v_cndmask_b32_e32 v16, v16, v193, vcc
	v_max_f32_e32 v32, v17, v17
	v_max_f32_e32 v33, v16, v16
	v_cndmask_b32_e32 v19, v19, v193, vcc
	v_cndmask_b32_e32 v18, v18, v193, vcc
	v_max_f32_e32 v32, v33, v32
	s_waitcnt lgkmcnt(0)
	v_mfma_f32_32x32x16_bf16 v[0:15], v[80:83], v[124:127], v[0:15]
	v_cndmask_b32_e32 v21, v21, v193, vcc
	v_cndmask_b32_e32 v20, v20, v193, vcc
	v_max3_f32 v32, v32, v18, v19
	v_cndmask_b32_e32 v23, v23, v193, vcc
	v_cndmask_b32_e32 v22, v22, v193, vcc
	v_max3_f32 v32, v32, v20, v21
	v_cndmask_b32_e32 v25, v25, v193, vcc
	v_cndmask_b32_e32 v24, v24, v193, vcc
	v_max3_f32 v32, v32, v22, v23
	v_cndmask_b32_e32 v27, v27, v193, vcc
	v_cndmask_b32_e32 v26, v26, v193, vcc
	v_max3_f32 v32, v32, v24, v25
	v_cndmask_b32_e32 v29, v29, v193, vcc
	v_cndmask_b32_e32 v28, v28, v193, vcc
	v_max3_f32 v32, v32, v26, v27
	v_cndmask_b32_e32 v31, v31, v193, vcc
	v_cndmask_b32_e32 v30, v30, v193, vcc
	v_max3_f32 v32, v32, v28, v29
	v_cndmask_b32_e32 v1, v1, v193, vcc
	v_cndmask_b32_e32 v0, v0, v193, vcc
	v_max3_f32 v32, v32, v30, v31
	v_cndmask_b32_e32 v3, v3, v193, vcc
	v_cndmask_b32_e32 v2, v2, v193, vcc
	v_max3_f32 v32, v32, v0, v1
	v_cndmask_b32_e32 v5, v5, v193, vcc
	v_cndmask_b32_e32 v4, v4, v193, vcc
	v_max3_f32 v32, v32, v2, v3
	v_cndmask_b32_e32 v7, v7, v193, vcc
	v_cndmask_b32_e32 v6, v6, v193, vcc
	v_max3_f32 v32, v32, v4, v5
	v_max3_f32 v32, v32, v6, v7
	v_max3_f32 v32, v32, v8, v9
	v_max3_f32 v32, v32, v10, v11
	v_max3_f32 v32, v32, v12, v13
	v_max3_f32 v32, v32, v14, v15
	v_mov_b32_e32 v33, v32
	s_nop 1
	v_permlane32_swap_b32_e32 v32, v33
	v_max_f32_e32 v33, v33, v33
	v_max_f32_e32 v32, v32, v32
	v_max_f32_e32 v32, v32, v33
	v_add_f32_e32 v33, 0x7149f2ca, v32
	v_mul_f32_e32 v33, 0x3db504f3, v33
	v_cmp_ge_f32_e32 vcc, s77, v33
	s_cmp_eq_u64 vcc, exec
	s_cbranch_scc0 .LBB0_1156
	v_mov_b32_e32 v198, 1.0
	v_mov_b32_e32 v204, 0xf149f2ca
	s_andn2_b64 vcc, exec, s[8:9]
	s_cbranch_vccnz .LBB0_981

.LBB0_987:
	s_waitcnt vmcnt(4)
	v_add_u32_e32 v76, 0x10900, v157
	ds_read_b128 v[80:83], v76
	ds_read_b128 v[84:87], v76 offset:32
	ds_read_b128 v[64:67], v76 offset:128
	ds_read_b128 v[68:71], v76 offset:160
	ds_read_b128 v[88:91], v76 offset:64
	ds_read_b128 v[72:75], v76 offset:192
	ds_read_b128 v[92:95], v76 offset:96
	ds_read_b128 v[76:79], v76 offset:224
	ds_read_b128 v[222:225], v189 offset:49152
	ds_read_b128 v[226:229], v189 offset:57344
	ds_read_b128 v[240:243], v190 offset:49152
	ds_read_b128 v[244:247], v190 offset:57344
	s_waitcnt lgkmcnt(2)
	v_mfma_f32_32x32x16_bf16 v[80:95], v[222:225], v[96:99], v[80:95]
	v_exp_f32_e32 v172, v172
	v_exp_f32_e32 v173, v173
	v_exp_f32_e32 v170, v170
	v_exp_f32_e32 v171, v171
	v_exp_f32_e32 v168, v168
	v_mfma_f32_32x32x16_bf16 v[64:79], v[226:229], v[96:99], v[64:79]
	ds_read_b128 v[222:225], v191 offset:49152
	ds_read_b128 v[226:229], v191 offset:57344
	v_exp_f32_e32 v169, v169
	v_exp_f32_e32 v203, v166
	v_exp_f32_e32 v206, v167
	v_exp_f32_e32 v238, v158
	v_add_f32_e32 v158, 0, v219
	s_waitcnt lgkmcnt(2)
	v_mfma_f32_32x32x16_bf16 v[64:79], v[244:247], v[100:103], v[64:79]
	v_add_f32_e32 v158, v221, v158
	v_add_f32_e32 v158, v217, v158
	v_add_f32_e32 v158, v220, v158
	v_add_f32_e32 v158, v216, v158
	v_add_f32_e32 v158, v218, v158
	v_mfma_f32_32x32x16_bf16 v[80:95], v[240:243], v[100:103], v[80:95]
	ds_read_b128 v[240:243], v192 offset:49152
	ds_read_b128 v[244:247], v192 offset:57344
	v_add_f32_e32 v158, v214, v158
	v_add_f32_e32 v158, v215, v158
	v_add_f32_e32 v158, v211, v158
	v_add_f32_e32 v158, v213, v158
	v_add_f32_e32 v158, v210, v158
	s_waitcnt lgkmcnt(2)
	v_mfma_f32_32x32x16_bf16 v[64:79], v[226:229], v[104:107], v[64:79]
	v_add_f32_e32 v158, v212, v158
	v_add_f32_e32 v158, v207, v158
	v_add_f32_e32 v158, v209, v158
	v_add_f32_e32 v158, v205, v158
	v_add_f32_e32 v158, v208, v158
	v_mfma_f32_32x32x16_bf16 v[80:95], v[222:225], v[104:107], v[80:95]
	ds_read_b128 v[222:225], v248 offset:49152
	ds_read_b128 v[226:229], v248 offset:57344
	v_add_f32_e32 v158, v172, v158
	v_add_f32_e32 v158, v173, v158
	v_add_f32_e32 v158, v170, v158
	v_add_f32_e32 v158, v171, v158
	v_exp_f32_e32 v232, v164
	s_waitcnt lgkmcnt(2)
	v_mfma_f32_32x32x16_bf16 v[64:79], v[244:247], v[108:111], v[64:79]
	v_add_f32_e32 v158, v168, v158
	v_exp_f32_e32 v233, v165
	v_add_f32_e32 v158, v169, v158
	v_exp_f32_e32 v234, v162
	v_add_f32_e32 v158, v203, v158
	v_mfma_f32_32x32x16_bf16 v[80:95], v[240:243], v[108:111], v[80:95]
	ds_read_b128 v[240:243], v249 offset:49152
	ds_read_b128 v[244:247], v249 offset:57344
	v_exp_f32_e32 v235, v163
	v_add_f32_e32 v158, v206, v158
	v_exp_f32_e32 v236, v160
	v_add_f32_e32 v158, v232, v158
	v_exp_f32_e32 v237, v161
	s_waitcnt lgkmcnt(2)
	v_mfma_f32_32x32x16_bf16 v[64:79], v[226:229], v[112:115], v[64:79]
	v_add_f32_e32 v158, v233, v158
	v_add_f32_e32 v158, v234, v158
	v_exp_f32_e32 v239, v159
	v_add_f32_e32 v158, v235, v158
	v_add_f32_e32 v158, v236, v158
	v_mfma_f32_32x32x16_bf16 v[80:95], v[222:225], v[112:115], v[80:95]
	ds_read_b128 v[222:225], v250 offset:49152
	ds_read_b128 v[226:229], v250 offset:57344
	v_add_f32_e32 v158, v237, v158
	v_add_f32_e32 v158, v238, v158
	v_add_f32_e32 v201, v239, v158
	v_mov_b32_e32 v202, v201
	s_nop 1
	s_waitcnt lgkmcnt(2)
	v_mfma_f32_32x32x16_bf16 v[64:79], v[244:247], v[116:119], v[64:79]
	v_permlane32_swap_b32_e32 v201, v202
	v_cvt_pk_bf16_f32 v158, v219, v221
	v_cvt_pk_bf16_f32 v159, v217, v220
	v_cvt_pk_bf16_f32 v160, v216, v218
	v_cvt_pk_bf16_f32 v161, v214, v215
	v_mfma_f32_32x32x16_bf16 v[80:95], v[240:243], v[116:119], v[80:95]
	ds_read_b128 v[240:243], v251 offset:49152
	ds_read_b128 v[244:247], v251 offset:57344
	v_cvt_pk_bf16_f32 v162, v211, v213
	v_cvt_pk_bf16_f32 v163, v210, v212
	v_cvt_pk_bf16_f32 v164, v207, v209
	v_cvt_pk_bf16_f32 v165, v205, v208
	v_cvt_pk_bf16_f32 v166, v172, v173
	s_waitcnt lgkmcnt(2)
	v_mfma_f32_32x32x16_bf16 v[64:79], v[226:229], v[120:123], v[64:79]
	v_cvt_pk_bf16_f32 v167, v170, v171
	v_cvt_pk_bf16_f32 v168, v168, v169
	v_cvt_pk_bf16_f32 v169, v203, v206
	v_cvt_pk_bf16_f32 v170, v232, v233
	v_cvt_pk_bf16_f32 v171, v234, v235
	v_mfma_f32_32x32x16_bf16 v[80:95], v[222:225], v[120:123], v[80:95]
	v_cvt_pk_bf16_f32 v172, v236, v237
	v_cvt_pk_bf16_f32 v173, v238, v239
	s_nop 0
	v_permlane32_swap_b32_e32 v158, v160
	v_permlane32_swap_b32_e32 v159, v161
	s_waitcnt lgkmcnt(0)
	v_mfma_f32_32x32x16_bf16 v[64:79], v[244:247], v[124:127], v[64:79]
	v_permlane32_swap_b32_e32 v162, v164
	v_permlane32_swap_b32_e32 v163, v165
	v_permlane32_swap_b32_e32 v166, v168
	v_permlane32_swap_b32_e32 v167, v169
	v_permlane32_swap_b32_e32 v170, v172
	v_mfma_f32_32x32x16_bf16 v[80:95], v[240:243], v[124:127], v[80:95]
	v_permlane32_swap_b32_e32 v171, v173
	s_setprio 1
	ds_read_b64_tr_b16 v[206:207], v180 offset:0
	ds_read_b64_tr_b16 v[208:209], v180 offset:0x800
	ds_read_b64_tr_b16 v[210:211], v180 offset:0x1000
	ds_read_b64_tr_b16 v[212:213], v180 offset:0x1800
	ds_read_b64_tr_b16 v[214:215], v180 offset:0x2000
	ds_read_b64_tr_b16 v[216:217], v180 offset:0x2800
	ds_read_b64_tr_b16 v[218:219], v180 offset:0x3000
	ds_read_b64_tr_b16 v[220:221], v180 offset:0x3800
	s_waitcnt lgkmcnt(0)
	s_nop 0
	v_mfma_f32_32x32x16_bf16 v[48:63], v[158:161], v[206:209], v[48:63]
	ds_read_b64_tr_b16 v[206:207], v180 offset:0x200
	ds_read_b64_tr_b16 v[208:209], v180 offset:0xa00
	v_mfma_f32_32x32x16_bf16 v[48:63], v[162:165], v[210:213], v[48:63]
	ds_read_b64_tr_b16 v[210:211], v180 offset:0x1200
	ds_read_b64_tr_b16 v[212:213], v180 offset:0x1a00
	v_mfma_f32_32x32x16_bf16 v[48:63], v[166:169], v[214:217], v[48:63]
	ds_read_b64_tr_b16 v[214:215], v180 offset:0x2200
	ds_read_b64_tr_b16 v[216:217], v180 offset:0x2a00
	ds_read_b64_tr_b16 v[222:223], v180 offset:0x3200
	ds_read_b64_tr_b16 v[224:225], v180 offset:0x3a00
	s_waitcnt lgkmcnt(0)
	v_mfma_f32_32x32x16_bf16 v[48:63], v[170:173], v[218:221], v[48:63]
	v_mfma_f32_32x32x16_bf16 v[32:47], v[158:161], v[206:209], v[32:47]
	ds_read_b64_tr_b16 v[206:207], v180 offset:0x400
	ds_read_b64_tr_b16 v[208:209], v180 offset:0xc00
	v_mfma_f32_32x32x16_bf16 v[32:47], v[162:165], v[210:213], v[32:47]
	ds_read_b64_tr_b16 v[210:211], v180 offset:0x1400
	ds_read_b64_tr_b16 v[212:213], v180 offset:0x1c00
	v_mfma_f32_32x32x16_bf16 v[32:47], v[166:169], v[214:217], v[32:47]
	ds_read_b64_tr_b16 v[214:215], v180 offset:0x2400
	ds_read_b64_tr_b16 v[216:217], v180 offset:0x2c00
	ds_read_b64_tr_b16 v[218:219], v180 offset:0x3400
	ds_read_b64_tr_b16 v[220:221], v180 offset:0x3c00
	s_waitcnt lgkmcnt(0)
	v_mfma_f32_32x32x16_bf16 v[32:47], v[170:173], v[222:225], v[32:47]
	v_mfma_f32_32x32x16_bf16 v[16:31], v[158:161], v[206:209], v[16:31]
	ds_read_b64_tr_b16 v[206:207], v180 offset:0x600
	ds_read_b64_tr_b16 v[208:209], v180 offset:0xe00
	v_mfma_f32_32x32x16_bf16 v[16:31], v[162:165], v[210:213], v[16:31]
	ds_read_b64_tr_b16 v[210:211], v180 offset:0x1600
	ds_read_b64_tr_b16 v[212:213], v180 offset:0x1e00
	v_mfma_f32_32x32x16_bf16 v[16:31], v[166:169], v[214:217], v[16:31]
	ds_read_b64_tr_b16 v[214:215], v180 offset:0x2600
	ds_read_b64_tr_b16 v[216:217], v180 offset:0x2e00
	ds_read_b64_tr_b16 v[222:223], v180 offset:0x3600
	ds_read_b64_tr_b16 v[224:225], v180 offset:0x3e00
	s_waitcnt lgkmcnt(0)
	v_mfma_f32_32x32x16_bf16 v[16:31], v[170:173], v[218:221], v[16:31]
	v_mfma_f32_32x32x16_bf16 v[0:15], v[158:161], v[206:209], v[0:15]
	v_mfma_f32_32x32x16_bf16 v[0:15], v[162:165], v[210:213], v[0:15]
	v_mfma_f32_32x32x16_bf16 v[0:15], v[166:169], v[214:217], v[0:15]
	v_mfma_f32_32x32x16_bf16 v[0:15], v[170:173], v[222:225], v[0:15]
	s_setprio 0
	s_add_i32 s0, s88, 0x7f
	s_cmp_le_i32 s0, s87
	s_cbranch_scc1 .LBB0_989
	v_add_u32_e32 v158, 0x4000007b, v199
	v_cmp_gt_u32_e32 vcc, 2.0, v158
	v_add_u32_e32 v158, 0x5b, v199
	s_nop 0
	v_cndmask_b32_e32 v80, v193, v80, vcc
	v_cmp_lt_u32_e32 vcc, s78, v158
	v_add_u32_e32 v158, 0x7a, v199
	s_nop 0
	v_cndmask_b32_e32 v64, v193, v64, vcc
	v_cmp_lt_u32_e32 vcc, s78, v158
	v_add_u32_e32 v158, 0x5a, v199
	s_nop 0
	v_cndmask_b32_e32 v81, v193, v81, vcc
	v_cmp_lt_u32_e32 vcc, s78, v158
	v_add_u32_e32 v158, 0x79, v199
	s_nop 0
	v_cndmask_b32_e32 v65, v193, v65, vcc
	v_cmp_lt_u32_e32 vcc, s78, v158
	v_add_u32_e32 v158, 0x59, v199
	s_nop 0
	v_cndmask_b32_e32 v82, v193, v82, vcc
	v_cmp_lt_u32_e32 vcc, s78, v158
	v_add_u32_e32 v158, 0x78, v199
	s_nop 0
	v_cndmask_b32_e32 v66, v193, v66, vcc
	v_cmp_lt_u32_e32 vcc, s78, v158
	v_add_u32_e32 v158, 0x58, v199
	s_nop 0
	v_cndmask_b32_e32 v83, v193, v83, vcc
	v_cmp_lt_u32_e32 vcc, s78, v158
	v_add_u32_e32 v158, 0x73, v199
	s_nop 0
	v_cndmask_b32_e32 v67, v193, v67, vcc
	v_cmp_lt_u32_e32 vcc, s78, v158
	v_add_u32_e32 v158, 0x53, v199
	s_nop 0
	v_cndmask_b32_e32 v84, v193, v84, vcc
	v_cmp_lt_u32_e32 vcc, s78, v158
	v_add_u32_e32 v158, 0x72, v199
	s_nop 0
	v_cndmask_b32_e32 v68, v193, v68, vcc
	v_cmp_lt_u32_e32 vcc, s78, v158
	v_add_u32_e32 v158, 0x52, v199
	s_nop 0
	v_cndmask_b32_e32 v85, v193, v85, vcc
	v_cmp_lt_u32_e32 vcc, s78, v158
	v_add_u32_e32 v158, 0x71, v199
	s_nop 0
	v_cndmask_b32_e32 v69, v193, v69, vcc
	v_cmp_lt_u32_e32 vcc, s78, v158
	v_add_u32_e32 v158, 0x51, v199
	s_nop 0
	v_cndmask_b32_e32 v86, v193, v86, vcc
	v_cmp_lt_u32_e32 vcc, s78, v158
	v_add_u32_e32 v158, 0x70, v199
	s_nop 0
	v_cndmask_b32_e32 v70, v193, v70, vcc
	v_cmp_lt_u32_e32 vcc, s78, v158
	v_add_u32_e32 v158, 0x50, v199
	s_nop 0
	v_cndmask_b32_e32 v87, v193, v87, vcc
	v_cmp_lt_u32_e32 vcc, s78, v158
	v_add_u32_e32 v158, 0x6b, v199
	s_nop 0
	v_cndmask_b32_e32 v71, v193, v71, vcc
	v_cmp_lt_u32_e32 vcc, s78, v158
	v_add_u32_e32 v158, 0x4b, v199
	s_nop 0
	v_cndmask_b32_e32 v88, v193, v88, vcc
	v_cmp_lt_u32_e32 vcc, s78, v158
	v_add_u32_e32 v158, 0x6a, v199
	s_nop 0
	v_cndmask_b32_e32 v72, v193, v72, vcc
	v_cmp_lt_u32_e32 vcc, s78, v158
	v_add_u32_e32 v158, 0x4a, v199
	s_nop 0
	v_cndmask_b32_e32 v89, v193, v89, vcc
	v_cmp_lt_u32_e32 vcc, s78, v158
	v_add_u32_e32 v158, 0x69, v199
	s_nop 0
	v_cndmask_b32_e32 v73, v193, v73, vcc
	v_cmp_lt_u32_e32 vcc, s78, v158
	v_add_u32_e32 v158, 0x49, v199
	s_nop 0
	v_cndmask_b32_e32 v90, v193, v90, vcc
	v_cmp_lt_u32_e32 vcc, s78, v158
	v_add_u32_e32 v158, 0x68, v199
	s_nop 0
	v_cndmask_b32_e32 v74, v193, v74, vcc
	v_cmp_lt_u32_e32 vcc, s78, v158
	v_add_u32_e32 v158, 0x48, v199
	s_nop 0
	v_cndmask_b32_e32 v91, v193, v91, vcc
	v_cmp_lt_u32_e32 vcc, s78, v158
	v_add_u32_e32 v158, 0x63, v199
	s_nop 0
	v_cndmask_b32_e32 v75, v193, v75, vcc
	v_cmp_lt_u32_e32 vcc, s78, v158
	v_add_u32_e32 v158, 0x43, v199
	s_nop 0
	v_cndmask_b32_e32 v92, v193, v92, vcc
	v_cmp_lt_u32_e32 vcc, s78, v158
	v_add_u32_e32 v158, 0x62, v199
	s_nop 0
	v_cndmask_b32_e32 v76, v193, v76, vcc
	v_cmp_lt_u32_e32 vcc, s78, v158
	v_add_u32_e32 v158, 0x42, v199
	s_nop 0
	v_cndmask_b32_e32 v93, v193, v93, vcc
	v_cmp_lt_u32_e32 vcc, s78, v158
	v_add_u32_e32 v158, 0x61, v199
	s_nop 0
	v_cndmask_b32_e32 v77, v193, v77, vcc
	v_cmp_lt_u32_e32 vcc, s78, v158
	v_add_u32_e32 v158, 0x41, v199
	s_nop 0
	v_cndmask_b32_e32 v94, v193, v94, vcc
	v_cmp_lt_u32_e32 vcc, s78, v158
	v_add_u32_e32 v158, 0x60, v199
	s_nop 0
	v_cndmask_b32_e32 v78, v193, v78, vcc
	v_cmp_lt_u32_e32 vcc, s78, v158
	v_add_u32_e32 v158, 64, v199
	s_nop 0
	v_cndmask_b32_e32 v95, v193, v95, vcc
	v_cmp_lt_u32_e32 vcc, s78, v158
	s_nop 1
	v_cndmask_b32_e32 v79, v193, v79, vcc

.LBB0_1000:
.LBB0_1001:
	ds_read_b128 v[80:83], v197
	ds_read_b128 v[84:87], v197 offset:32
	ds_read_b128 v[64:67], v197 offset:128
	ds_read_b128 v[68:71], v197 offset:160
	ds_read_b128 v[88:91], v197 offset:64
	ds_read_b128 v[72:75], v197 offset:192
	ds_read_b128 v[92:95], v197 offset:96
	ds_read_b128 v[76:79], v197 offset:224
	ds_read_b128 v[222:225], v189 offset:32768
	ds_read_b128 v[226:229], v189 offset:40960
	ds_read_b128 v[240:243], v190 offset:32768
	ds_read_b128 v[244:247], v190 offset:40960
	s_waitcnt lgkmcnt(2)
	v_mfma_f32_32x32x16_bf16 v[80:95], v[222:225], v[96:99], v[80:95]
	v_exp_f32_e32 v215, v215
	v_exp_f32_e32 v216, v216
	v_exp_f32_e32 v217, v217
	v_exp_f32_e32 v218, v218
	v_exp_f32_e32 v219, v219
	v_mfma_f32_32x32x16_bf16 v[64:79], v[226:229], v[96:99], v[64:79]
	ds_read_b128 v[222:225], v191 offset:32768
	ds_read_b128 v[226:229], v191 offset:40960
	v_exp_f32_e32 v208, v208
	v_exp_f32_e32 v209, v209
	v_exp_f32_e32 v210, v210
	v_exp_f32_e32 v211, v211
	v_exp_f32_e32 v212, v212
	s_waitcnt lgkmcnt(2)
	v_mfma_f32_32x32x16_bf16 v[80:95], v[240:243], v[100:103], v[80:95]
	v_exp_f32_e32 v213, v213
	v_exp_f32_e32 v214, v214
	v_exp_f32_e32 v220, v220
	v_exp_f32_e32 v221, v221
	v_exp_f32_e32 v235, v205
	v_mfma_f32_32x32x16_bf16 v[64:79], v[244:247], v[100:103], v[64:79]
	ds_read_b128 v[240:243], v192 offset:32768
	ds_read_b128 v[244:247], v192 offset:40960
	v_add_f32_e32 v205, 0, v172
	v_add_f32_e32 v205, v204, v205
	v_add_f32_e32 v205, v170, v205
	v_add_f32_e32 v205, v173, v205
	v_add_f32_e32 v205, v169, v205
	s_waitcnt lgkmcnt(2)
	v_mfma_f32_32x32x16_bf16 v[80:95], v[222:225], v[104:107], v[80:95]
	v_add_f32_e32 v205, v171, v205
	v_add_f32_e32 v205, v167, v205
	v_add_f32_e32 v205, v168, v205
	v_add_f32_e32 v205, v164, v205
	v_add_f32_e32 v205, v166, v205
	v_mfma_f32_32x32x16_bf16 v[64:79], v[226:229], v[104:107], v[64:79]
	ds_read_b128 v[222:225], v248 offset:32768
	ds_read_b128 v[226:229], v248 offset:40960
	v_add_f32_e32 v205, v163, v205
	v_add_f32_e32 v205, v165, v205
	v_add_f32_e32 v205, v160, v205
	v_add_f32_e32 v205, v162, v205
	v_add_f32_e32 v205, v159, v205
	s_waitcnt lgkmcnt(2)
	v_mfma_f32_32x32x16_bf16 v[80:95], v[240:243], v[108:111], v[80:95]
	v_add_f32_e32 v205, v161, v205
	v_add_f32_e32 v205, v215, v205
	v_add_f32_e32 v205, v216, v205
	v_add_f32_e32 v205, v217, v205
	v_add_f32_e32 v205, v218, v205
	v_mfma_f32_32x32x16_bf16 v[64:79], v[244:247], v[108:111], v[64:79]
	ds_read_b128 v[240:243], v249 offset:32768
	ds_read_b128 v[244:247], v249 offset:40960
	v_add_f32_e32 v205, v219, v205
	v_add_f32_e32 v205, v208, v205
	v_add_f32_e32 v205, v209, v205
	v_add_f32_e32 v205, v210, v205
	v_exp_f32_e32 v234, v207
	s_waitcnt lgkmcnt(2)
	v_mfma_f32_32x32x16_bf16 v[80:95], v[222:225], v[112:115], v[80:95]
	v_add_f32_e32 v205, v211, v205
	v_add_f32_e32 v205, v212, v205
	v_add_f32_e32 v205, v213, v205
	v_add_f32_e32 v205, v214, v205
	v_add_f32_e32 v205, v234, v205
	v_mfma_f32_32x32x16_bf16 v[64:79], v[226:229], v[112:115], v[64:79]
	ds_read_b128 v[222:225], v250 offset:32768
	ds_read_b128 v[226:229], v250 offset:40960
	v_add_f32_e32 v205, v220, v205
	v_add_f32_e32 v205, v221, v205
	v_add_f32_e32 v232, v235, v205
	v_mov_b32_e32 v233, v232
	s_nop 1
	s_waitcnt lgkmcnt(2)
	v_mfma_f32_32x32x16_bf16 v[80:95], v[240:243], v[116:119], v[80:95]
	v_permlane32_swap_b32_e32 v232, v233
	v_cvt_pk_bf16_f32 v204, v172, v204
	v_cvt_pk_bf16_f32 v205, v170, v173
	v_cvt_pk_bf16_f32 v206, v169, v171
	v_cvt_pk_bf16_f32 v207, v167, v168
	v_mfma_f32_32x32x16_bf16 v[64:79], v[244:247], v[116:119], v[64:79]
	ds_read_b128 v[240:243], v251 offset:32768
	ds_read_b128 v[244:247], v251 offset:40960
	v_cvt_pk_bf16_f32 v164, v164, v166
	v_cvt_pk_bf16_f32 v165, v163, v165
	v_cvt_pk_bf16_f32 v166, v160, v162
	v_cvt_pk_bf16_f32 v167, v159, v161
	v_cvt_pk_bf16_f32 v160, v215, v216
	s_waitcnt lgkmcnt(2)
	v_mfma_f32_32x32x16_bf16 v[80:95], v[222:225], v[120:123], v[80:95]
	v_cvt_pk_bf16_f32 v161, v217, v218
	v_cvt_pk_bf16_f32 v162, v219, v208
	v_cvt_pk_bf16_f32 v163, v209, v210
	v_cvt_pk_bf16_f32 v168, v211, v212
	v_cvt_pk_bf16_f32 v169, v213, v214
	v_mfma_f32_32x32x16_bf16 v[64:79], v[226:229], v[120:123], v[64:79]
	v_cvt_pk_bf16_f32 v170, v234, v220
	v_cvt_pk_bf16_f32 v171, v221, v235
	s_nop 0
	v_permlane32_swap_b32_e32 v204, v206
	v_permlane32_swap_b32_e32 v205, v207
	s_waitcnt lgkmcnt(0)
	v_mfma_f32_32x32x16_bf16 v[80:95], v[240:243], v[124:127], v[80:95]
	v_permlane32_swap_b32_e32 v164, v166
	v_permlane32_swap_b32_e32 v165, v167
	v_permlane32_swap_b32_e32 v160, v162
	v_permlane32_swap_b32_e32 v161, v163
	v_permlane32_swap_b32_e32 v168, v170
	v_mfma_f32_32x32x16_bf16 v[64:79], v[244:247], v[124:127], v[64:79]
	v_permlane32_swap_b32_e32 v169, v171
	s_setprio 1
	ds_read_b64_tr_b16 v[208:209], v180 offset:0x4000
	ds_read_b64_tr_b16 v[210:211], v180 offset:0x4800
	ds_read_b64_tr_b16 v[212:213], v180 offset:0x5000
	ds_read_b64_tr_b16 v[214:215], v180 offset:0x5800
	ds_read_b64_tr_b16 v[216:217], v180 offset:0x6000
	ds_read_b64_tr_b16 v[218:219], v180 offset:0x6800
	ds_read_b64_tr_b16 v[224:225], v180 offset:0x7000
	ds_read_b64_tr_b16 v[226:227], v180 offset:0x7800
	s_waitcnt lgkmcnt(0)
	s_nop 0
	v_mfma_f32_32x32x16_bf16 v[48:63], v[204:207], v[208:211], v[48:63]
	ds_read_b64_tr_b16 v[208:209], v180 offset:0x4200
	ds_read_b64_tr_b16 v[210:211], v180 offset:0x4a00
	v_mfma_f32_32x32x16_bf16 v[48:63], v[164:167], v[212:215], v[48:63]
	ds_read_b64_tr_b16 v[212:213], v180 offset:0x5200
	ds_read_b64_tr_b16 v[214:215], v180 offset:0x5a00
	v_mfma_f32_32x32x16_bf16 v[48:63], v[160:163], v[216:219], v[48:63]
	ds_read_b64_tr_b16 v[216:217], v180 offset:0x6200
	ds_read_b64_tr_b16 v[218:219], v180 offset:0x6a00
	ds_read_b64_tr_b16 v[228:229], v180 offset:0x7200
	ds_read_b64_tr_b16 v[230:231], v180 offset:0x7a00
	s_waitcnt lgkmcnt(0)
	v_mfma_f32_32x32x16_bf16 v[48:63], v[168:171], v[224:227], v[48:63]
	v_mfma_f32_32x32x16_bf16 v[32:47], v[204:207], v[208:211], v[32:47]
	ds_read_b64_tr_b16 v[208:209], v180 offset:0x4400
	ds_read_b64_tr_b16 v[210:211], v180 offset:0x4c00
	v_mfma_f32_32x32x16_bf16 v[32:47], v[164:167], v[212:215], v[32:47]
	ds_read_b64_tr_b16 v[212:213], v180 offset:0x5400
	ds_read_b64_tr_b16 v[214:215], v180 offset:0x5c00
	v_mfma_f32_32x32x16_bf16 v[32:47], v[160:163], v[216:219], v[32:47]
	ds_read_b64_tr_b16 v[216:217], v180 offset:0x6400
	ds_read_b64_tr_b16 v[218:219], v180 offset:0x6c00
	ds_read_b64_tr_b16 v[224:225], v180 offset:0x7400
	ds_read_b64_tr_b16 v[226:227], v180 offset:0x7c00
	s_waitcnt lgkmcnt(0)
	v_mfma_f32_32x32x16_bf16 v[32:47], v[168:171], v[228:231], v[32:47]
	v_mfma_f32_32x32x16_bf16 v[16:31], v[204:207], v[208:211], v[16:31]
	ds_read_b64_tr_b16 v[208:209], v180 offset:0x4600
	ds_read_b64_tr_b16 v[210:211], v180 offset:0x4e00
	v_mfma_f32_32x32x16_bf16 v[16:31], v[164:167], v[212:215], v[16:31]
	ds_read_b64_tr_b16 v[212:213], v180 offset:0x5600
	ds_read_b64_tr_b16 v[214:215], v180 offset:0x5e00
	v_mfma_f32_32x32x16_bf16 v[16:31], v[160:163], v[216:219], v[16:31]
	ds_read_b64_tr_b16 v[216:217], v180 offset:0x6600
	ds_read_b64_tr_b16 v[218:219], v180 offset:0x6e00
	ds_read_b64_tr_b16 v[228:229], v180 offset:0x7600
	ds_read_b64_tr_b16 v[230:231], v180 offset:0x7e00
	s_waitcnt lgkmcnt(0)
	v_mfma_f32_32x32x16_bf16 v[16:31], v[168:171], v[224:227], v[16:31]
	v_mfma_f32_32x32x16_bf16 v[0:15], v[204:207], v[208:211], v[0:15]
	v_mfma_f32_32x32x16_bf16 v[0:15], v[164:167], v[212:215], v[0:15]
	v_mfma_f32_32x32x16_bf16 v[0:15], v[160:163], v[216:219], v[0:15]
	v_mfma_f32_32x32x16_bf16 v[0:15], v[168:171], v[228:231], v[0:15]
	s_setprio 0
	s_add_i32 s0, s88, 0xbf
	s_cmp_le_i32 s0, s87
	s_cbranch_scc1 .LBB0_1003
	v_add_u32_e32 v159, 0x4000003b, v199
	v_cmp_gt_u32_e32 vcc, 2.0, v159
	v_add_u32_e32 v159, 27, v199
	s_nop 0
	v_cndmask_b32_e32 v80, v193, v80, vcc
	v_cmp_lt_u32_e32 vcc, s78, v159
	v_add_u32_e32 v159, 58, v199
	s_nop 0
	v_cndmask_b32_e32 v64, v193, v64, vcc
	v_cmp_lt_u32_e32 vcc, s78, v159
	v_add_u32_e32 v159, 26, v199
	s_nop 0
	v_cndmask_b32_e32 v81, v193, v81, vcc
	v_cmp_lt_u32_e32 vcc, s78, v159
	v_add_u32_e32 v159, 57, v199
	s_nop 0
	v_cndmask_b32_e32 v65, v193, v65, vcc
	v_cmp_lt_u32_e32 vcc, s78, v159
	v_add_u32_e32 v159, 25, v199
	s_nop 0
	v_cndmask_b32_e32 v82, v193, v82, vcc
	v_cmp_lt_u32_e32 vcc, s78, v159
	v_add_u32_e32 v159, 56, v199
	s_nop 0
	v_cndmask_b32_e32 v66, v193, v66, vcc
	v_cmp_lt_u32_e32 vcc, s78, v159
	v_add_u32_e32 v159, 24, v199
	s_nop 0
	v_cndmask_b32_e32 v83, v193, v83, vcc
	v_cmp_lt_u32_e32 vcc, s78, v159
	v_add_u32_e32 v159, 51, v199
	s_nop 0
	v_cndmask_b32_e32 v67, v193, v67, vcc
	v_cmp_lt_u32_e32 vcc, s78, v159
	v_add_u32_e32 v159, 19, v199
	s_nop 0
	v_cndmask_b32_e32 v84, v193, v84, vcc
	v_cmp_lt_u32_e32 vcc, s78, v159
	v_add_u32_e32 v159, 50, v199
	s_nop 0
	v_cndmask_b32_e32 v68, v193, v68, vcc
	v_cmp_lt_u32_e32 vcc, s78, v159
	v_add_u32_e32 v159, 18, v199
	s_nop 0
	v_cndmask_b32_e32 v85, v193, v85, vcc
	v_cmp_lt_u32_e32 vcc, s78, v159
	v_add_u32_e32 v159, 49, v199
	s_nop 0
	v_cndmask_b32_e32 v69, v193, v69, vcc
	v_cmp_lt_u32_e32 vcc, s78, v159
	v_add_u32_e32 v159, 17, v199
	s_nop 0
	v_cndmask_b32_e32 v86, v193, v86, vcc
	v_cmp_lt_u32_e32 vcc, s78, v159
	v_add_u32_e32 v159, 48, v199
	s_nop 0
	v_cndmask_b32_e32 v70, v193, v70, vcc
	v_cmp_lt_u32_e32 vcc, s78, v159
	v_add_u32_e32 v159, 16, v199
	s_nop 0
	v_cndmask_b32_e32 v87, v193, v87, vcc
	v_cmp_lt_u32_e32 vcc, s78, v159
	v_add_u32_e32 v159, 43, v199
	s_nop 0
	v_cndmask_b32_e32 v71, v193, v71, vcc
	v_cmp_lt_u32_e32 vcc, s78, v159
	v_add_u32_e32 v159, 11, v199
	s_nop 0
	v_cndmask_b32_e32 v88, v193, v88, vcc
	v_cmp_lt_u32_e32 vcc, s78, v159
	v_add_u32_e32 v159, 42, v199
	s_nop 0
	v_cndmask_b32_e32 v72, v193, v72, vcc
	v_cmp_lt_u32_e32 vcc, s78, v159
	v_add_u32_e32 v159, 10, v199
	s_nop 0
	v_cndmask_b32_e32 v89, v193, v89, vcc
	v_cmp_lt_u32_e32 vcc, s78, v159
	v_add_u32_e32 v159, 41, v199
	s_nop 0
	v_cndmask_b32_e32 v73, v193, v73, vcc
	v_cmp_lt_u32_e32 vcc, s78, v159
	v_add_u32_e32 v159, 9, v199
	s_nop 0
	v_cndmask_b32_e32 v90, v193, v90, vcc
	v_cmp_lt_u32_e32 vcc, s78, v159
	v_add_u32_e32 v159, 40, v199
	s_nop 0
	v_cndmask_b32_e32 v74, v193, v74, vcc
	v_cmp_lt_u32_e32 vcc, s78, v159
	v_add_u32_e32 v159, 8, v199
	s_nop 0
	v_cndmask_b32_e32 v91, v193, v91, vcc
	v_cmp_lt_u32_e32 vcc, s78, v159
	v_add_u32_e32 v159, 35, v199
	s_nop 0
	v_cndmask_b32_e32 v75, v193, v75, vcc
	v_cmp_lt_u32_e32 vcc, s78, v159
	v_add_u32_e32 v159, 3, v199
	s_nop 0
	v_cndmask_b32_e32 v92, v193, v92, vcc
	v_cmp_lt_u32_e32 vcc, s78, v159
	v_add_u32_e32 v159, 34, v199
	s_nop 0
	v_cndmask_b32_e32 v76, v193, v76, vcc
	v_cmp_lt_u32_e32 vcc, s78, v159
	v_add_u32_e32 v159, 2, v199
	s_nop 0
	v_cndmask_b32_e32 v93, v193, v93, vcc
	v_cmp_lt_u32_e32 vcc, s78, v159
	v_add_u32_e32 v159, 33, v199
	s_nop 0
	v_cndmask_b32_e32 v77, v193, v77, vcc
	v_cmp_lt_u32_e32 vcc, s78, v159
	v_add_u32_e32 v159, 1, v199
	s_nop 0
	v_cndmask_b32_e32 v94, v193, v94, vcc
	v_cmp_lt_u32_e32 vcc, s78, v159
	v_add_u32_e32 v159, 32, v199
	s_nop 0
	v_cndmask_b32_e32 v78, v193, v78, vcc
	v_cmp_lt_u32_e32 vcc, s78, v159
	s_nop 1
	v_cndmask_b32_e32 v95, v193, v95, vcc
	v_cmp_lt_u32_e32 vcc, s78, v199
	s_nop 1
	v_cndmask_b32_e32 v79, v193, v79, vcc

.LBB0_1010:
	v_cndmask_b32_e64 v204, v129, v158, s[10:11]
	v_mul_f32_e32 v130, 0xbe0293ee, v204
	v_mov_b32_e32 v129, v130
	v_fmamk_f32 v80, v80, 0x3e0293ee, v130
	v_fmamk_f32 v81, v81, 0x3e0293ee, v130
	v_fmamk_f32 v82, v82, 0x3e0293ee, v130
	v_fmamk_f32 v83, v83, 0x3e0293ee, v130
	v_fmamk_f32 v84, v84, 0x3e0293ee, v130
	v_fmamk_f32 v85, v85, 0x3e0293ee, v130
	v_fmamk_f32 v86, v86, 0x3e0293ee, v130
	v_fmamk_f32 v87, v87, 0x3e0293ee, v130
	v_fmamk_f32 v88, v88, 0x3e0293ee, v130
	v_fmamk_f32 v89, v89, 0x3e0293ee, v130
	v_fmamk_f32 v90, v90, 0x3e0293ee, v130
	v_fmamk_f32 v91, v91, 0x3e0293ee, v130
	v_fmamk_f32 v92, v92, 0x3e0293ee, v130
	v_fmamk_f32 v93, v93, 0x3e0293ee, v130
	v_fmamk_f32 v94, v94, 0x3e0293ee, v130
	v_fmac_f32_e32 v129, 0x3e0293ee, v95
	v_exp_f32_e32 v219, v80
	v_exp_f32_e32 v221, v81
	v_exp_f32_e32 v217, v82
	v_exp_f32_e32 v220, v83
	v_exp_f32_e32 v216, v84
	v_exp_f32_e32 v218, v85
	v_exp_f32_e32 v214, v86
	v_exp_f32_e32 v215, v87
	v_exp_f32_e32 v211, v88
	v_exp_f32_e32 v213, v89
	v_exp_f32_e32 v210, v90
	v_exp_f32_e32 v212, v91
	v_exp_f32_e32 v207, v92
	v_exp_f32_e32 v209, v93
	v_exp_f32_e32 v205, v94
	v_exp_f32_e32 v208, v129
	v_pk_fma_f32 v[172:173], v[64:65], s[30:31], v[130:131] op_sel_hi:[1,0,0]
	v_add_f32_e32 v64, v201, v202
	v_fmac_f32_e32 v64, v198, v155
	v_add_f32_e32 v155, v232, v233
	s_addk_i32 s88, 0x80
	s_add_i32 s8, s89, 2
	s_add_i32 s0, s89, 1
	v_pk_fma_f32 v[158:159], v[78:79], s[30:31], v[130:131] op_sel_hi:[1,0,0]
	v_pk_fma_f32 v[160:161], v[76:77], s[30:31], v[130:131] op_sel_hi:[1,0,0]
	v_pk_fma_f32 v[162:163], v[74:75], s[30:31], v[130:131] op_sel_hi:[1,0,0]
	v_pk_fma_f32 v[164:165], v[72:73], s[30:31], v[130:131] op_sel_hi:[1,0,0]
	v_pk_fma_f32 v[166:167], v[70:71], s[30:31], v[130:131] op_sel_hi:[1,0,0]
	v_pk_fma_f32 v[168:169], v[68:69], s[30:31], v[130:131] op_sel_hi:[1,0,0]
	v_pk_fma_f32 v[170:171], v[66:67], s[30:31], v[130:131] op_sel_hi:[1,0,0]
	v_fmac_f32_e32 v155, v64, v203
	s_cmp_ge_i32 s0, s23
	v_add_u32_e32 v199, 0xffffff80, v199
	s_waitcnt lgkmcnt(0)
	s_barrier
	s_cbranch_scc1 .LBB0_1015
	s_mov_b32 s89, s8
	v_mov_b32_e32 v198, v128
	s_branch .LBB0_983

.LBB0_1190:
	s_add_u32 s61, s4, 0x2fa04000
	v_and_b32_e32 v4, 0xfffff0, v175
	v_lshlrev_b32_e32 v5, 1, v175
	s_addc_u32 s62, s5, 0
	v_and_or_b32 v4, v5, 8, v4
	s_add_u32 s63, s4, 0x2fa05000
	v_lshrrev_b32_e32 v4, 1, v4
	v_lshrrev_b32_e32 v6, 5, v144
	s_addc_u32 s64, s5, 0
	v_lshrrev_b32_e32 v5, 1, v175
	v_or_b32_e32 v4, v4, v6
	v_bfe_u32 v6, v145, 4, 2
	s_add_u32 s65, s4, 0x2fa02000
	v_and_or_b32 v5, v5, 4, v6
	v_and_b32_e32 v6, 48, v177
	s_addc_u32 s66, s5, 0
	v_lshl_or_b32 v5, v5, 6, v6
	s_add_u32 s67, s4, 0x2fa03000
	v_lshl_or_b32 v5, v4, 9, v5
	v_lshlrev_b32_e32 v4, 4, v176
	s_addc_u32 s68, s5, 0
	v_or_b32_e32 v1, v1, v0
	v_lshlrev_b32_e32 v0, 3, v176
	v_and_b32_e32 v4, 0xc0, v4
	v_lshlrev_b32_e32 v6, 1, v176
	v_and_or_b32 v4, v0, 24, v4
	v_and_b32_e32 v6, 32, v6
	v_and_b32_e32 v0, 0x100, v0
	s_cmp_lg_u32 0, -1
	v_lshrrev_b32_e32 v3, 5, v176
	v_or3_b32 v0, v4, v6, v0
	s_cselect_b32 s0, 0, 0
	v_add_u32_e32 v180, s0, v0
	v_lshlrev_b32_e32 v182, 4, v3
	v_lshlrev_b32_e32 v0, 4, v174
	v_and_b32_e32 v0, 0xf0, v0
	v_or_b32_e32 v4, 32, v182
	v_xad_u32 v10, v4, v0, 0
	v_or_b32_e32 v4, 64, v182
	v_xad_u32 v11, v4, v0, 0
	v_or_b32_e32 v4, 0x60, v182
	v_lshlrev_b32_e32 v178, 2, v3
	v_xad_u32 v9, v182, v0, 0
	v_xad_u32 v12, v4, v0, 0
	s_add_i32 s0, 0, 0x10800
	v_and_b32_e32 v0, 1, v2
	v_mul_u32_u24_e32 v184, 0x440, v3
	v_lshrrev_b32_e32 v3, 4, v176
	v_lshl_add_u32 v183, v176, 2, s0
	v_cmp_eq_u32_e64 s[6:7], 0, v0
	s_movk_i32 s0, 0x1800
	v_mul_u32_u24_e32 v0, 0x1800, v3
	v_mov_b32_e32 v4, 0x1e000
	v_mov_b32_e32 v6, 0x24000
	v_mov_b32_e32 v8, 0x2a000
	v_lshlrev_b32_e32 v7, 8, v174
	v_mul_u32_u24_e32 v185, 0x110, v3
	v_or_b32_e32 v2, 0x18000, v0
	v_mad_u32_u24 v4, v3, s0, v4
	v_mad_u32_u24 v6, v3, s0, v6
	v_mad_u32_u24 v8, v3, s0, v8
	v_sub_u32_e32 v3, v174, v178
	s_mov_b32 s21, 0
	v_or_b32_e32 v181, 0x60000, v144
	v_cmp_gt_u32_e64 s[4:5], 32, v176
	v_mov_b32_e32 v147, 0
	s_mov_b32 s69, 0x18000
	s_mov_b32 s70, 0x24000
	v_add_u32_e32 v186, 0xbfffff45, v3
	s_movk_i32 s71, 0x6000
	s_movk_i32 s75, 0x3000
	s_mov_b32 s76, 0x41000000
	s_mov_b32 s30, 0x3e0293ee
	s_brev_b32 s77, -3
	v_lshlrev_b32_e32 v146, 1, v144
	v_lshlrev_b32_e32 v148, 1, v0
	s_mov_b32 s78, 0xc000
	v_lshlrev_b32_e32 v150, 1, v2
	v_lshlrev_b32_e32 v152, 1, v4
	v_lshlrev_b32_e32 v154, 1, v6
	v_lshlrev_b32_e32 v156, 1, v8
	v_add_u32_e32 v187, 0, v5
	v_mov_b32_e32 v188, 0x3fd0
	v_add_u32_e32 v189, v9, v7
	v_xor_b32_e32 v248, 0x80, v189
	v_add_u32_e32 v190, v10, v7
	v_xor_b32_e32 v249, 0x80, v190
	v_add_u32_e32 v191, v11, v7
	v_xor_b32_e32 v250, 0x80, v191
	v_add_u32_e32 v192, v12, v7
	v_xor_b32_e32 v251, 0x80, v192
	v_mov_b32_e32 v193, 0xff800000
	v_add_u32_e32 v194, 0, v1
	s_waitcnt lgkmcnt(0)
	s_barrier
	s_branch .LBB0_1193

.LBB0_1207:
	v_add_u32_e32 v157, 0, v182
	v_add_u32_e32 v197, 0x10800, v157
	ds_read_b128 v[0:3], v189 offset:32768
	ds_read_b128 v[16:19], v197
	ds_read_b128 v[20:23], v197 offset:32
	ds_read_b128 v[24:27], v197 offset:64
	ds_read_b128 v[28:31], v197 offset:96
	ds_read_b128 v[32:35], v189 offset:40960
	ds_read_b128 v[36:39], v248 offset:32768
	s_cmp_eq_u32 s83, 0
	s_waitcnt vmcnt(15) lgkmcnt(2)
	v_mfma_f32_32x32x16_bf16 v[16:31], v[0:3], v[96:99], v[16:31]
	ds_read_b128 v[0:3], v197 offset:128
	ds_read_b128 v[4:7], v197 offset:160
	ds_read_b128 v[8:11], v197 offset:192
	ds_read_b128 v[12:15], v197 offset:224
	ds_read_b128 v[40:43], v248 offset:40960
	s_cselect_b64 vcc, -1, 0
	s_waitcnt lgkmcnt(1)
	v_mfma_f32_32x32x16_bf16 v[0:15], v[32:35], v[96:99], v[0:15]
	ds_read_b128 v[32:35], v190 offset:32768
	ds_read_b128 v[44:47], v249 offset:32768
	s_waitcnt vmcnt(14) lgkmcnt(1)
	v_mfma_f32_32x32x16_bf16 v[16:31], v[32:35], v[100:103], v[16:31]
	ds_read_b128 v[32:35], v190 offset:40960
	ds_read_b128 v[48:51], v249 offset:40960
	s_waitcnt lgkmcnt(1)
	v_mfma_f32_32x32x16_bf16 v[0:15], v[32:35], v[100:103], v[0:15]
	ds_read_b128 v[32:35], v191 offset:32768
	ds_read_b128 v[52:55], v250 offset:32768
	s_waitcnt vmcnt(13) lgkmcnt(1)
	v_mfma_f32_32x32x16_bf16 v[16:31], v[32:35], v[104:107], v[16:31]
	ds_read_b128 v[32:35], v191 offset:40960
	ds_read_b128 v[56:59], v250 offset:40960
	s_waitcnt lgkmcnt(1)
	v_mfma_f32_32x32x16_bf16 v[0:15], v[32:35], v[104:107], v[0:15]
	ds_read_b128 v[32:35], v192 offset:32768
	ds_read_b128 v[60:63], v251 offset:32768
	s_waitcnt vmcnt(12) lgkmcnt(1)
	v_mfma_f32_32x32x16_bf16 v[16:31], v[32:35], v[108:111], v[16:31]
	ds_read_b128 v[32:35], v192 offset:40960
	ds_read_b128 v[80:83], v251 offset:40960
	s_waitcnt vmcnt(11)
	v_mfma_f32_32x32x16_bf16 v[16:31], v[36:39], v[112:115], v[16:31]
	s_waitcnt lgkmcnt(1)
	v_mfma_f32_32x32x16_bf16 v[0:15], v[32:35], v[108:111], v[0:15]
	s_waitcnt vmcnt(10)
	v_mfma_f32_32x32x16_bf16 v[16:31], v[44:47], v[116:119], v[16:31]
	v_mfma_f32_32x32x16_bf16 v[0:15], v[40:43], v[112:115], v[0:15]
	s_waitcnt vmcnt(9)
	v_mfma_f32_32x32x16_bf16 v[16:31], v[52:55], v[120:123], v[16:31]
	v_mfma_f32_32x32x16_bf16 v[0:15], v[48:51], v[116:119], v[0:15]
	s_waitcnt vmcnt(8)
	v_mfma_f32_32x32x16_bf16 v[16:31], v[60:63], v[124:127], v[16:31]
	v_mfma_f32_32x32x16_bf16 v[0:15], v[56:59], v[120:123], v[0:15]
	s_nop 10
	v_cndmask_b32_e32 v17, v17, v193, vcc
	v_cndmask_b32_e32 v16, v16, v193, vcc
	v_max_f32_e32 v32, v17, v17
	v_max_f32_e32 v33, v16, v16
	v_cndmask_b32_e32 v19, v19, v193, vcc
	v_cndmask_b32_e32 v18, v18, v193, vcc
	v_max_f32_e32 v32, v33, v32
	s_waitcnt lgkmcnt(0)
	v_mfma_f32_32x32x16_bf16 v[0:15], v[80:83], v[124:127], v[0:15]
	v_cndmask_b32_e32 v21, v21, v193, vcc
	v_cndmask_b32_e32 v20, v20, v193, vcc
	v_max3_f32 v32, v32, v18, v19
	v_cndmask_b32_e32 v23, v23, v193, vcc
	v_cndmask_b32_e32 v22, v22, v193, vcc
	v_max3_f32 v32, v32, v20, v21
	v_cndmask_b32_e32 v25, v25, v193, vcc
	v_cndmask_b32_e32 v24, v24, v193, vcc
	v_max3_f32 v32, v32, v22, v23
	v_cndmask_b32_e32 v27, v27, v193, vcc
	v_cndmask_b32_e32 v26, v26, v193, vcc
	v_max3_f32 v32, v32, v24, v25
	v_cndmask_b32_e32 v29, v29, v193, vcc
	v_cndmask_b32_e32 v28, v28, v193, vcc
	v_max3_f32 v32, v32, v26, v27
	v_cndmask_b32_e32 v31, v31, v193, vcc
	v_cndmask_b32_e32 v30, v30, v193, vcc
	v_max3_f32 v32, v32, v28, v29
	v_cndmask_b32_e32 v1, v1, v193, vcc
	v_cndmask_b32_e32 v0, v0, v193, vcc
	v_max3_f32 v32, v32, v30, v31
	v_cndmask_b32_e32 v3, v3, v193, vcc
	v_cndmask_b32_e32 v2, v2, v193, vcc
	v_max3_f32 v32, v32, v0, v1
	v_cndmask_b32_e32 v5, v5, v193, vcc
	v_cndmask_b32_e32 v4, v4, v193, vcc
	v_max3_f32 v32, v32, v2, v3
	v_cndmask_b32_e32 v7, v7, v193, vcc
	v_cndmask_b32_e32 v6, v6, v193, vcc
	v_max3_f32 v32, v32, v4, v5
	v_max3_f32 v32, v32, v6, v7
	v_max3_f32 v32, v32, v8, v9
	v_max3_f32 v32, v32, v10, v11
	v_max3_f32 v32, v32, v12, v13
	v_max3_f32 v32, v32, v14, v15
	v_mov_b32_e32 v33, v32
	s_nop 1
	v_permlane32_swap_b32_e32 v32, v33
	v_max_f32_e32 v33, v33, v33
	v_max_f32_e32 v32, v32, v32
	v_max_f32_e32 v32, v32, v33
	v_add_f32_e32 v33, 0x7149f2ca, v32
	v_mul_f32_e32 v33, 0x3db504f3, v33
	v_cmp_ge_f32_e32 vcc, s76, v33
	s_cmp_eq_u64 vcc, exec
	s_cbranch_scc0 .LBB0_1386
	v_mov_b32_e32 v198, 1.0
	v_mov_b32_e32 v204, 0xf149f2ca
	s_andn2_b64 vcc, exec, s[8:9]
	s_cbranch_vccnz .LBB0_1211

.LBB0_1217:
	s_waitcnt vmcnt(4)
	v_add_u32_e32 v76, 0x10900, v157
	ds_read_b128 v[80:83], v76
	ds_read_b128 v[84:87], v76 offset:32
	ds_read_b128 v[64:67], v76 offset:128
	ds_read_b128 v[68:71], v76 offset:160
	ds_read_b128 v[88:91], v76 offset:64
	ds_read_b128 v[72:75], v76 offset:192
	ds_read_b128 v[92:95], v76 offset:96
	ds_read_b128 v[76:79], v76 offset:224
	ds_read_b128 v[222:225], v189 offset:49152
	ds_read_b128 v[226:229], v189 offset:57344
	ds_read_b128 v[240:243], v190 offset:49152
	ds_read_b128 v[244:247], v190 offset:57344
	s_waitcnt lgkmcnt(2)
	v_mfma_f32_32x32x16_bf16 v[80:95], v[222:225], v[96:99], v[80:95]
	v_exp_f32_e32 v172, v172
	v_exp_f32_e32 v173, v173
	v_exp_f32_e32 v170, v170
	v_exp_f32_e32 v171, v171
	v_exp_f32_e32 v168, v168
	v_mfma_f32_32x32x16_bf16 v[64:79], v[226:229], v[96:99], v[64:79]
	ds_read_b128 v[222:225], v191 offset:49152
	ds_read_b128 v[226:229], v191 offset:57344
	v_exp_f32_e32 v169, v169
	v_exp_f32_e32 v203, v166
	v_exp_f32_e32 v206, v167
	v_exp_f32_e32 v238, v158
	v_add_f32_e32 v158, 0, v219
	s_waitcnt lgkmcnt(2)
	v_mfma_f32_32x32x16_bf16 v[64:79], v[244:247], v[100:103], v[64:79]
	v_add_f32_e32 v158, v221, v158
	v_add_f32_e32 v158, v217, v158
	v_add_f32_e32 v158, v220, v158
	v_add_f32_e32 v158, v216, v158
	v_add_f32_e32 v158, v218, v158
	v_mfma_f32_32x32x16_bf16 v[80:95], v[240:243], v[100:103], v[80:95]
	ds_read_b128 v[240:243], v192 offset:49152
	ds_read_b128 v[244:247], v192 offset:57344
	v_add_f32_e32 v158, v214, v158
	v_add_f32_e32 v158, v215, v158
	v_add_f32_e32 v158, v211, v158
	v_add_f32_e32 v158, v213, v158
	v_add_f32_e32 v158, v210, v158
	s_waitcnt lgkmcnt(2)
	v_mfma_f32_32x32x16_bf16 v[64:79], v[226:229], v[104:107], v[64:79]
	v_add_f32_e32 v158, v212, v158
	v_add_f32_e32 v158, v207, v158
	v_add_f32_e32 v158, v209, v158
	v_add_f32_e32 v158, v205, v158
	v_add_f32_e32 v158, v208, v158
	v_mfma_f32_32x32x16_bf16 v[80:95], v[222:225], v[104:107], v[80:95]
	ds_read_b128 v[222:225], v248 offset:49152
	ds_read_b128 v[226:229], v248 offset:57344
	v_add_f32_e32 v158, v172, v158
	v_add_f32_e32 v158, v173, v158
	v_add_f32_e32 v158, v170, v158
	v_add_f32_e32 v158, v171, v158
	v_exp_f32_e32 v232, v164
	s_waitcnt lgkmcnt(2)
	v_mfma_f32_32x32x16_bf16 v[64:79], v[244:247], v[108:111], v[64:79]
	v_add_f32_e32 v158, v168, v158
	v_exp_f32_e32 v233, v165
	v_add_f32_e32 v158, v169, v158
	v_exp_f32_e32 v234, v162
	v_add_f32_e32 v158, v203, v158
	v_mfma_f32_32x32x16_bf16 v[80:95], v[240:243], v[108:111], v[80:95]
	ds_read_b128 v[240:243], v249 offset:49152
	ds_read_b128 v[244:247], v249 offset:57344
	v_exp_f32_e32 v235, v163
	v_add_f32_e32 v158, v206, v158
	v_exp_f32_e32 v236, v160
	v_add_f32_e32 v158, v232, v158
	v_exp_f32_e32 v237, v161
	s_waitcnt lgkmcnt(2)
	v_mfma_f32_32x32x16_bf16 v[64:79], v[226:229], v[112:115], v[64:79]
	v_add_f32_e32 v158, v233, v158
	v_add_f32_e32 v158, v234, v158
	v_exp_f32_e32 v239, v159
	v_add_f32_e32 v158, v235, v158
	v_add_f32_e32 v158, v236, v158
	v_mfma_f32_32x32x16_bf16 v[80:95], v[222:225], v[112:115], v[80:95]
	ds_read_b128 v[222:225], v250 offset:49152
	ds_read_b128 v[226:229], v250 offset:57344
	v_add_f32_e32 v158, v237, v158
	v_add_f32_e32 v158, v238, v158
	v_add_f32_e32 v201, v239, v158
	v_mov_b32_e32 v202, v201
	s_nop 1
	s_waitcnt lgkmcnt(2)
	v_mfma_f32_32x32x16_bf16 v[64:79], v[244:247], v[116:119], v[64:79]
	v_permlane32_swap_b32_e32 v201, v202
	v_cvt_pk_bf16_f32 v158, v219, v221
	v_cvt_pk_bf16_f32 v159, v217, v220
	v_cvt_pk_bf16_f32 v160, v216, v218
	v_cvt_pk_bf16_f32 v161, v214, v215
	v_mfma_f32_32x32x16_bf16 v[80:95], v[240:243], v[116:119], v[80:95]
	ds_read_b128 v[240:243], v251 offset:49152
	ds_read_b128 v[244:247], v251 offset:57344
	v_cvt_pk_bf16_f32 v162, v211, v213
	v_cvt_pk_bf16_f32 v163, v210, v212
	v_cvt_pk_bf16_f32 v164, v207, v209
	v_cvt_pk_bf16_f32 v165, v205, v208
	v_cvt_pk_bf16_f32 v166, v172, v173
	s_waitcnt lgkmcnt(2)
	v_mfma_f32_32x32x16_bf16 v[64:79], v[226:229], v[120:123], v[64:79]
	v_cvt_pk_bf16_f32 v167, v170, v171
	v_cvt_pk_bf16_f32 v168, v168, v169
	v_cvt_pk_bf16_f32 v169, v203, v206
	v_cvt_pk_bf16_f32 v170, v232, v233
	v_cvt_pk_bf16_f32 v171, v234, v235
	v_mfma_f32_32x32x16_bf16 v[80:95], v[222:225], v[120:123], v[80:95]
	v_cvt_pk_bf16_f32 v172, v236, v237
	v_cvt_pk_bf16_f32 v173, v238, v239
	s_nop 0
	v_permlane32_swap_b32_e32 v158, v160
	v_permlane32_swap_b32_e32 v159, v161
	s_waitcnt lgkmcnt(0)
	v_mfma_f32_32x32x16_bf16 v[64:79], v[244:247], v[124:127], v[64:79]
	v_permlane32_swap_b32_e32 v162, v164
	v_permlane32_swap_b32_e32 v163, v165
	v_permlane32_swap_b32_e32 v166, v168
	v_permlane32_swap_b32_e32 v167, v169
	v_permlane32_swap_b32_e32 v170, v172
	v_mfma_f32_32x32x16_bf16 v[80:95], v[240:243], v[124:127], v[80:95]
	v_permlane32_swap_b32_e32 v171, v173
	s_setprio 1
	ds_read_b64_tr_b16 v[206:207], v180 offset:0
	ds_read_b64_tr_b16 v[208:209], v180 offset:0x800
	ds_read_b64_tr_b16 v[210:211], v180 offset:0x1000
	ds_read_b64_tr_b16 v[212:213], v180 offset:0x1800
	ds_read_b64_tr_b16 v[214:215], v180 offset:0x2000
	ds_read_b64_tr_b16 v[216:217], v180 offset:0x2800
	ds_read_b64_tr_b16 v[218:219], v180 offset:0x3000
	ds_read_b64_tr_b16 v[220:221], v180 offset:0x3800
	s_waitcnt lgkmcnt(0)
	s_nop 0
	v_mfma_f32_32x32x16_bf16 v[48:63], v[158:161], v[206:209], v[48:63]
	ds_read_b64_tr_b16 v[206:207], v180 offset:0x200
	ds_read_b64_tr_b16 v[208:209], v180 offset:0xa00
	v_mfma_f32_32x32x16_bf16 v[48:63], v[162:165], v[210:213], v[48:63]
	ds_read_b64_tr_b16 v[210:211], v180 offset:0x1200
	ds_read_b64_tr_b16 v[212:213], v180 offset:0x1a00
	v_mfma_f32_32x32x16_bf16 v[48:63], v[166:169], v[214:217], v[48:63]
	ds_read_b64_tr_b16 v[214:215], v180 offset:0x2200
	ds_read_b64_tr_b16 v[216:217], v180 offset:0x2a00
	ds_read_b64_tr_b16 v[222:223], v180 offset:0x3200
	ds_read_b64_tr_b16 v[224:225], v180 offset:0x3a00
	s_waitcnt lgkmcnt(0)
	v_mfma_f32_32x32x16_bf16 v[48:63], v[170:173], v[218:221], v[48:63]
	v_mfma_f32_32x32x16_bf16 v[32:47], v[158:161], v[206:209], v[32:47]
	ds_read_b64_tr_b16 v[206:207], v180 offset:0x400
	ds_read_b64_tr_b16 v[208:209], v180 offset:0xc00
	v_mfma_f32_32x32x16_bf16 v[32:47], v[162:165], v[210:213], v[32:47]
	ds_read_b64_tr_b16 v[210:211], v180 offset:0x1400
	ds_read_b64_tr_b16 v[212:213], v180 offset:0x1c00
	v_mfma_f32_32x32x16_bf16 v[32:47], v[166:169], v[214:217], v[32:47]
	ds_read_b64_tr_b16 v[214:215], v180 offset:0x2400
	ds_read_b64_tr_b16 v[216:217], v180 offset:0x2c00
	ds_read_b64_tr_b16 v[218:219], v180 offset:0x3400
	ds_read_b64_tr_b16 v[220:221], v180 offset:0x3c00
	s_waitcnt lgkmcnt(0)
	v_mfma_f32_32x32x16_bf16 v[32:47], v[170:173], v[222:225], v[32:47]
	v_mfma_f32_32x32x16_bf16 v[16:31], v[158:161], v[206:209], v[16:31]
	ds_read_b64_tr_b16 v[206:207], v180 offset:0x600
	ds_read_b64_tr_b16 v[208:209], v180 offset:0xe00
	v_mfma_f32_32x32x16_bf16 v[16:31], v[162:165], v[210:213], v[16:31]
	ds_read_b64_tr_b16 v[210:211], v180 offset:0x1600
	ds_read_b64_tr_b16 v[212:213], v180 offset:0x1e00
	v_mfma_f32_32x32x16_bf16 v[16:31], v[166:169], v[214:217], v[16:31]
	ds_read_b64_tr_b16 v[214:215], v180 offset:0x2600
	ds_read_b64_tr_b16 v[216:217], v180 offset:0x2e00
	ds_read_b64_tr_b16 v[222:223], v180 offset:0x3600
	ds_read_b64_tr_b16 v[224:225], v180 offset:0x3e00
	s_waitcnt lgkmcnt(0)
	v_mfma_f32_32x32x16_bf16 v[16:31], v[170:173], v[218:221], v[16:31]
	v_mfma_f32_32x32x16_bf16 v[0:15], v[158:161], v[206:209], v[0:15]
	v_mfma_f32_32x32x16_bf16 v[0:15], v[162:165], v[210:213], v[0:15]
	v_mfma_f32_32x32x16_bf16 v[0:15], v[166:169], v[214:217], v[0:15]
	v_mfma_f32_32x32x16_bf16 v[0:15], v[170:173], v[222:225], v[0:15]
	s_setprio 0
	s_add_i32 s0, s87, 0x7f
	s_cmp_le_i32 s0, s86
	s_cbranch_scc1 .LBB0_1219
	v_add_u32_e32 v158, 0x4000007b, v199
	v_cmp_gt_u32_e32 vcc, 2.0, v158
	v_add_u32_e32 v158, 0x5b, v199
	s_nop 0
	v_cndmask_b32_e32 v80, v193, v80, vcc
	v_cmp_lt_u32_e32 vcc, s77, v158
	v_add_u32_e32 v158, 0x7a, v199
	s_nop 0
	v_cndmask_b32_e32 v64, v193, v64, vcc
	v_cmp_lt_u32_e32 vcc, s77, v158
	v_add_u32_e32 v158, 0x5a, v199
	s_nop 0
	v_cndmask_b32_e32 v81, v193, v81, vcc
	v_cmp_lt_u32_e32 vcc, s77, v158
	v_add_u32_e32 v158, 0x79, v199
	s_nop 0
	v_cndmask_b32_e32 v65, v193, v65, vcc
	v_cmp_lt_u32_e32 vcc, s77, v158
	v_add_u32_e32 v158, 0x59, v199
	s_nop 0
	v_cndmask_b32_e32 v82, v193, v82, vcc
	v_cmp_lt_u32_e32 vcc, s77, v158
	v_add_u32_e32 v158, 0x78, v199
	s_nop 0
	v_cndmask_b32_e32 v66, v193, v66, vcc
	v_cmp_lt_u32_e32 vcc, s77, v158
	v_add_u32_e32 v158, 0x58, v199
	s_nop 0
	v_cndmask_b32_e32 v83, v193, v83, vcc
	v_cmp_lt_u32_e32 vcc, s77, v158
	v_add_u32_e32 v158, 0x73, v199
	s_nop 0
	v_cndmask_b32_e32 v67, v193, v67, vcc
	v_cmp_lt_u32_e32 vcc, s77, v158
	v_add_u32_e32 v158, 0x53, v199
	s_nop 0
	v_cndmask_b32_e32 v84, v193, v84, vcc
	v_cmp_lt_u32_e32 vcc, s77, v158
	v_add_u32_e32 v158, 0x72, v199
	s_nop 0
	v_cndmask_b32_e32 v68, v193, v68, vcc
	v_cmp_lt_u32_e32 vcc, s77, v158
	v_add_u32_e32 v158, 0x52, v199
	s_nop 0
	v_cndmask_b32_e32 v85, v193, v85, vcc
	v_cmp_lt_u32_e32 vcc, s77, v158
	v_add_u32_e32 v158, 0x71, v199
	s_nop 0
	v_cndmask_b32_e32 v69, v193, v69, vcc
	v_cmp_lt_u32_e32 vcc, s77, v158
	v_add_u32_e32 v158, 0x51, v199
	s_nop 0
	v_cndmask_b32_e32 v86, v193, v86, vcc
	v_cmp_lt_u32_e32 vcc, s77, v158
	v_add_u32_e32 v158, 0x70, v199
	s_nop 0
	v_cndmask_b32_e32 v70, v193, v70, vcc
	v_cmp_lt_u32_e32 vcc, s77, v158
	v_add_u32_e32 v158, 0x50, v199
	s_nop 0
	v_cndmask_b32_e32 v87, v193, v87, vcc
	v_cmp_lt_u32_e32 vcc, s77, v158
	v_add_u32_e32 v158, 0x6b, v199
	s_nop 0
	v_cndmask_b32_e32 v71, v193, v71, vcc
	v_cmp_lt_u32_e32 vcc, s77, v158
	v_add_u32_e32 v158, 0x4b, v199
	s_nop 0
	v_cndmask_b32_e32 v88, v193, v88, vcc
	v_cmp_lt_u32_e32 vcc, s77, v158
	v_add_u32_e32 v158, 0x6a, v199
	s_nop 0
	v_cndmask_b32_e32 v72, v193, v72, vcc
	v_cmp_lt_u32_e32 vcc, s77, v158
	v_add_u32_e32 v158, 0x4a, v199
	s_nop 0
	v_cndmask_b32_e32 v89, v193, v89, vcc
	v_cmp_lt_u32_e32 vcc, s77, v158
	v_add_u32_e32 v158, 0x69, v199
	s_nop 0
	v_cndmask_b32_e32 v73, v193, v73, vcc
	v_cmp_lt_u32_e32 vcc, s77, v158
	v_add_u32_e32 v158, 0x49, v199
	s_nop 0
	v_cndmask_b32_e32 v90, v193, v90, vcc
	v_cmp_lt_u32_e32 vcc, s77, v158
	v_add_u32_e32 v158, 0x68, v199
	s_nop 0
	v_cndmask_b32_e32 v74, v193, v74, vcc
	v_cmp_lt_u32_e32 vcc, s77, v158
	v_add_u32_e32 v158, 0x48, v199
	s_nop 0
	v_cndmask_b32_e32 v91, v193, v91, vcc
	v_cmp_lt_u32_e32 vcc, s77, v158
	v_add_u32_e32 v158, 0x63, v199
	s_nop 0
	v_cndmask_b32_e32 v75, v193, v75, vcc
	v_cmp_lt_u32_e32 vcc, s77, v158
	v_add_u32_e32 v158, 0x43, v199
	s_nop 0
	v_cndmask_b32_e32 v92, v193, v92, vcc
	v_cmp_lt_u32_e32 vcc, s77, v158
	v_add_u32_e32 v158, 0x62, v199
	s_nop 0
	v_cndmask_b32_e32 v76, v193, v76, vcc
	v_cmp_lt_u32_e32 vcc, s77, v158
	v_add_u32_e32 v158, 0x42, v199
	s_nop 0
	v_cndmask_b32_e32 v93, v193, v93, vcc
	v_cmp_lt_u32_e32 vcc, s77, v158
	v_add_u32_e32 v158, 0x61, v199
	s_nop 0
	v_cndmask_b32_e32 v77, v193, v77, vcc
	v_cmp_lt_u32_e32 vcc, s77, v158
	v_add_u32_e32 v158, 0x41, v199
	s_nop 0
	v_cndmask_b32_e32 v94, v193, v94, vcc
	v_cmp_lt_u32_e32 vcc, s77, v158
	v_add_u32_e32 v158, 0x60, v199
	s_nop 0
	v_cndmask_b32_e32 v78, v193, v78, vcc
	v_cmp_lt_u32_e32 vcc, s77, v158
	v_add_u32_e32 v158, 64, v199
	s_nop 0
	v_cndmask_b32_e32 v95, v193, v95, vcc
	v_cmp_lt_u32_e32 vcc, s77, v158
	s_nop 1
	v_cndmask_b32_e32 v79, v193, v79, vcc

.LBB0_1230:
.LBB0_1231:
	ds_read_b128 v[80:83], v197
	ds_read_b128 v[84:87], v197 offset:32
	ds_read_b128 v[64:67], v197 offset:128
	ds_read_b128 v[68:71], v197 offset:160
	ds_read_b128 v[88:91], v197 offset:64
	ds_read_b128 v[72:75], v197 offset:192
	ds_read_b128 v[92:95], v197 offset:96
	ds_read_b128 v[76:79], v197 offset:224
	ds_read_b128 v[222:225], v189 offset:32768
	ds_read_b128 v[226:229], v189 offset:40960
	ds_read_b128 v[240:243], v190 offset:32768
	ds_read_b128 v[244:247], v190 offset:40960
	s_waitcnt lgkmcnt(2)
	v_mfma_f32_32x32x16_bf16 v[80:95], v[222:225], v[96:99], v[80:95]
	v_exp_f32_e32 v215, v215
	v_exp_f32_e32 v216, v216
	v_exp_f32_e32 v217, v217
	v_exp_f32_e32 v218, v218
	v_exp_f32_e32 v219, v219
	v_mfma_f32_32x32x16_bf16 v[64:79], v[226:229], v[96:99], v[64:79]
	ds_read_b128 v[222:225], v191 offset:32768
	ds_read_b128 v[226:229], v191 offset:40960
	v_exp_f32_e32 v208, v208
	v_exp_f32_e32 v209, v209
	v_exp_f32_e32 v210, v210
	v_exp_f32_e32 v211, v211
	v_exp_f32_e32 v212, v212
	s_waitcnt lgkmcnt(2)
	v_mfma_f32_32x32x16_bf16 v[80:95], v[240:243], v[100:103], v[80:95]
	v_exp_f32_e32 v213, v213
	v_exp_f32_e32 v214, v214
	v_exp_f32_e32 v220, v220
	v_exp_f32_e32 v221, v221
	v_exp_f32_e32 v235, v205
	v_mfma_f32_32x32x16_bf16 v[64:79], v[244:247], v[100:103], v[64:79]
	ds_read_b128 v[240:243], v192 offset:32768
	ds_read_b128 v[244:247], v192 offset:40960
	v_add_f32_e32 v205, 0, v172
	v_add_f32_e32 v205, v204, v205
	v_add_f32_e32 v205, v170, v205
	v_add_f32_e32 v205, v173, v205
	v_add_f32_e32 v205, v169, v205
	s_waitcnt lgkmcnt(2)
	v_mfma_f32_32x32x16_bf16 v[80:95], v[222:225], v[104:107], v[80:95]
	v_add_f32_e32 v205, v171, v205
	v_add_f32_e32 v205, v167, v205
	v_add_f32_e32 v205, v168, v205
	v_add_f32_e32 v205, v164, v205
	v_add_f32_e32 v205, v166, v205
	v_mfma_f32_32x32x16_bf16 v[64:79], v[226:229], v[104:107], v[64:79]
	ds_read_b128 v[222:225], v248 offset:32768
	ds_read_b128 v[226:229], v248 offset:40960
	v_add_f32_e32 v205, v163, v205
	v_add_f32_e32 v205, v165, v205
	v_add_f32_e32 v205, v160, v205
	v_add_f32_e32 v205, v162, v205
	v_add_f32_e32 v205, v159, v205
	s_waitcnt lgkmcnt(2)
	v_mfma_f32_32x32x16_bf16 v[80:95], v[240:243], v[108:111], v[80:95]
	v_add_f32_e32 v205, v161, v205
	v_add_f32_e32 v205, v215, v205
	v_add_f32_e32 v205, v216, v205
	v_add_f32_e32 v205, v217, v205
	v_add_f32_e32 v205, v218, v205
	v_mfma_f32_32x32x16_bf16 v[64:79], v[244:247], v[108:111], v[64:79]
	ds_read_b128 v[240:243], v249 offset:32768
	ds_read_b128 v[244:247], v249 offset:40960
	v_add_f32_e32 v205, v219, v205
	v_add_f32_e32 v205, v208, v205
	v_add_f32_e32 v205, v209, v205
	v_add_f32_e32 v205, v210, v205
	v_exp_f32_e32 v234, v207
	s_waitcnt lgkmcnt(2)
	v_mfma_f32_32x32x16_bf16 v[80:95], v[222:225], v[112:115], v[80:95]
	v_add_f32_e32 v205, v211, v205
	v_add_f32_e32 v205, v212, v205
	v_add_f32_e32 v205, v213, v205
	v_add_f32_e32 v205, v214, v205
	v_add_f32_e32 v205, v234, v205
	v_mfma_f32_32x32x16_bf16 v[64:79], v[226:229], v[112:115], v[64:79]
	ds_read_b128 v[222:225], v250 offset:32768
	ds_read_b128 v[226:229], v250 offset:40960
	v_add_f32_e32 v205, v220, v205
	v_add_f32_e32 v205, v221, v205
	v_add_f32_e32 v232, v235, v205
	v_mov_b32_e32 v233, v232
	s_nop 1
	s_waitcnt lgkmcnt(2)
	v_mfma_f32_32x32x16_bf16 v[80:95], v[240:243], v[116:119], v[80:95]
	v_permlane32_swap_b32_e32 v232, v233
	v_cvt_pk_bf16_f32 v204, v172, v204
	v_cvt_pk_bf16_f32 v205, v170, v173
	v_cvt_pk_bf16_f32 v206, v169, v171
	v_cvt_pk_bf16_f32 v207, v167, v168
	v_mfma_f32_32x32x16_bf16 v[64:79], v[244:247], v[116:119], v[64:79]
	ds_read_b128 v[240:243], v251 offset:32768
	ds_read_b128 v[244:247], v251 offset:40960
	v_cvt_pk_bf16_f32 v164, v164, v166
	v_cvt_pk_bf16_f32 v165, v163, v165
	v_cvt_pk_bf16_f32 v166, v160, v162
	v_cvt_pk_bf16_f32 v167, v159, v161
	v_cvt_pk_bf16_f32 v160, v215, v216
	s_waitcnt lgkmcnt(2)
	v_mfma_f32_32x32x16_bf16 v[80:95], v[222:225], v[120:123], v[80:95]
	v_cvt_pk_bf16_f32 v161, v217, v218
	v_cvt_pk_bf16_f32 v162, v219, v208
	v_cvt_pk_bf16_f32 v163, v209, v210
	v_cvt_pk_bf16_f32 v168, v211, v212
	v_cvt_pk_bf16_f32 v169, v213, v214
	v_mfma_f32_32x32x16_bf16 v[64:79], v[226:229], v[120:123], v[64:79]
	v_cvt_pk_bf16_f32 v170, v234, v220
	v_cvt_pk_bf16_f32 v171, v221, v235
	s_nop 0
	v_permlane32_swap_b32_e32 v204, v206
	v_permlane32_swap_b32_e32 v205, v207
	s_waitcnt lgkmcnt(0)
	v_mfma_f32_32x32x16_bf16 v[80:95], v[240:243], v[124:127], v[80:95]
	v_permlane32_swap_b32_e32 v164, v166
	v_permlane32_swap_b32_e32 v165, v167
	v_permlane32_swap_b32_e32 v160, v162
	v_permlane32_swap_b32_e32 v161, v163
	v_permlane32_swap_b32_e32 v168, v170
	v_mfma_f32_32x32x16_bf16 v[64:79], v[244:247], v[124:127], v[64:79]
	v_permlane32_swap_b32_e32 v169, v171
	s_setprio 1
	ds_read_b64_tr_b16 v[208:209], v180 offset:0x4000
	ds_read_b64_tr_b16 v[210:211], v180 offset:0x4800
	ds_read_b64_tr_b16 v[212:213], v180 offset:0x5000
	ds_read_b64_tr_b16 v[214:215], v180 offset:0x5800
	ds_read_b64_tr_b16 v[216:217], v180 offset:0x6000
	ds_read_b64_tr_b16 v[218:219], v180 offset:0x6800
	ds_read_b64_tr_b16 v[224:225], v180 offset:0x7000
	ds_read_b64_tr_b16 v[226:227], v180 offset:0x7800
	s_waitcnt lgkmcnt(0)
	s_nop 0
	v_mfma_f32_32x32x16_bf16 v[48:63], v[204:207], v[208:211], v[48:63]
	ds_read_b64_tr_b16 v[208:209], v180 offset:0x4200
	ds_read_b64_tr_b16 v[210:211], v180 offset:0x4a00
	v_mfma_f32_32x32x16_bf16 v[48:63], v[164:167], v[212:215], v[48:63]
	ds_read_b64_tr_b16 v[212:213], v180 offset:0x5200
	ds_read_b64_tr_b16 v[214:215], v180 offset:0x5a00
	v_mfma_f32_32x32x16_bf16 v[48:63], v[160:163], v[216:219], v[48:63]
	ds_read_b64_tr_b16 v[216:217], v180 offset:0x6200
	ds_read_b64_tr_b16 v[218:219], v180 offset:0x6a00
	ds_read_b64_tr_b16 v[228:229], v180 offset:0x7200
	ds_read_b64_tr_b16 v[230:231], v180 offset:0x7a00
	s_waitcnt lgkmcnt(0)
	v_mfma_f32_32x32x16_bf16 v[48:63], v[168:171], v[224:227], v[48:63]
	v_mfma_f32_32x32x16_bf16 v[32:47], v[204:207], v[208:211], v[32:47]
	ds_read_b64_tr_b16 v[208:209], v180 offset:0x4400
	ds_read_b64_tr_b16 v[210:211], v180 offset:0x4c00
	v_mfma_f32_32x32x16_bf16 v[32:47], v[164:167], v[212:215], v[32:47]
	ds_read_b64_tr_b16 v[212:213], v180 offset:0x5400
	ds_read_b64_tr_b16 v[214:215], v180 offset:0x5c00
	v_mfma_f32_32x32x16_bf16 v[32:47], v[160:163], v[216:219], v[32:47]
	ds_read_b64_tr_b16 v[216:217], v180 offset:0x6400
	ds_read_b64_tr_b16 v[218:219], v180 offset:0x6c00
	ds_read_b64_tr_b16 v[224:225], v180 offset:0x7400
	ds_read_b64_tr_b16 v[226:227], v180 offset:0x7c00
	s_waitcnt lgkmcnt(0)
	v_mfma_f32_32x32x16_bf16 v[32:47], v[168:171], v[228:231], v[32:47]
	v_mfma_f32_32x32x16_bf16 v[16:31], v[204:207], v[208:211], v[16:31]
	ds_read_b64_tr_b16 v[208:209], v180 offset:0x4600
	ds_read_b64_tr_b16 v[210:211], v180 offset:0x4e00
	v_mfma_f32_32x32x16_bf16 v[16:31], v[164:167], v[212:215], v[16:31]
	ds_read_b64_tr_b16 v[212:213], v180 offset:0x5600
	ds_read_b64_tr_b16 v[214:215], v180 offset:0x5e00
	v_mfma_f32_32x32x16_bf16 v[16:31], v[160:163], v[216:219], v[16:31]
	ds_read_b64_tr_b16 v[216:217], v180 offset:0x6600
	ds_read_b64_tr_b16 v[218:219], v180 offset:0x6e00
	ds_read_b64_tr_b16 v[228:229], v180 offset:0x7600
	ds_read_b64_tr_b16 v[230:231], v180 offset:0x7e00
	s_waitcnt lgkmcnt(0)
	v_mfma_f32_32x32x16_bf16 v[16:31], v[168:171], v[224:227], v[16:31]
	v_mfma_f32_32x32x16_bf16 v[0:15], v[204:207], v[208:211], v[0:15]
	v_mfma_f32_32x32x16_bf16 v[0:15], v[164:167], v[212:215], v[0:15]
	v_mfma_f32_32x32x16_bf16 v[0:15], v[160:163], v[216:219], v[0:15]
	v_mfma_f32_32x32x16_bf16 v[0:15], v[168:171], v[228:231], v[0:15]
	s_setprio 0
	s_add_i32 s0, s87, 0xbf
	s_cmp_le_i32 s0, s86
	s_cbranch_scc1 .LBB0_1233
	v_add_u32_e32 v159, 0x4000003b, v199
	v_cmp_gt_u32_e32 vcc, 2.0, v159
	v_add_u32_e32 v159, 27, v199
	s_nop 0
	v_cndmask_b32_e32 v80, v193, v80, vcc
	v_cmp_lt_u32_e32 vcc, s77, v159
	v_add_u32_e32 v159, 58, v199
	s_nop 0
	v_cndmask_b32_e32 v64, v193, v64, vcc
	v_cmp_lt_u32_e32 vcc, s77, v159
	v_add_u32_e32 v159, 26, v199
	s_nop 0
	v_cndmask_b32_e32 v81, v193, v81, vcc
	v_cmp_lt_u32_e32 vcc, s77, v159
	v_add_u32_e32 v159, 57, v199
	s_nop 0
	v_cndmask_b32_e32 v65, v193, v65, vcc
	v_cmp_lt_u32_e32 vcc, s77, v159
	v_add_u32_e32 v159, 25, v199
	s_nop 0
	v_cndmask_b32_e32 v82, v193, v82, vcc
	v_cmp_lt_u32_e32 vcc, s77, v159
	v_add_u32_e32 v159, 56, v199
	s_nop 0
	v_cndmask_b32_e32 v66, v193, v66, vcc
	v_cmp_lt_u32_e32 vcc, s77, v159
	v_add_u32_e32 v159, 24, v199
	s_nop 0
	v_cndmask_b32_e32 v83, v193, v83, vcc
	v_cmp_lt_u32_e32 vcc, s77, v159
	v_add_u32_e32 v159, 51, v199
	s_nop 0
	v_cndmask_b32_e32 v67, v193, v67, vcc
	v_cmp_lt_u32_e32 vcc, s77, v159
	v_add_u32_e32 v159, 19, v199
	s_nop 0
	v_cndmask_b32_e32 v84, v193, v84, vcc
	v_cmp_lt_u32_e32 vcc, s77, v159
	v_add_u32_e32 v159, 50, v199
	s_nop 0
	v_cndmask_b32_e32 v68, v193, v68, vcc
	v_cmp_lt_u32_e32 vcc, s77, v159
	v_add_u32_e32 v159, 18, v199
	s_nop 0
	v_cndmask_b32_e32 v85, v193, v85, vcc
	v_cmp_lt_u32_e32 vcc, s77, v159
	v_add_u32_e32 v159, 49, v199
	s_nop 0
	v_cndmask_b32_e32 v69, v193, v69, vcc
	v_cmp_lt_u32_e32 vcc, s77, v159
	v_add_u32_e32 v159, 17, v199
	s_nop 0
	v_cndmask_b32_e32 v86, v193, v86, vcc
	v_cmp_lt_u32_e32 vcc, s77, v159
	v_add_u32_e32 v159, 48, v199
	s_nop 0
	v_cndmask_b32_e32 v70, v193, v70, vcc
	v_cmp_lt_u32_e32 vcc, s77, v159
	v_add_u32_e32 v159, 16, v199
	s_nop 0
	v_cndmask_b32_e32 v87, v193, v87, vcc
	v_cmp_lt_u32_e32 vcc, s77, v159
	v_add_u32_e32 v159, 43, v199
	s_nop 0
	v_cndmask_b32_e32 v71, v193, v71, vcc
	v_cmp_lt_u32_e32 vcc, s77, v159
	v_add_u32_e32 v159, 11, v199
	s_nop 0
	v_cndmask_b32_e32 v88, v193, v88, vcc
	v_cmp_lt_u32_e32 vcc, s77, v159
	v_add_u32_e32 v159, 42, v199
	s_nop 0
	v_cndmask_b32_e32 v72, v193, v72, vcc
	v_cmp_lt_u32_e32 vcc, s77, v159
	v_add_u32_e32 v159, 10, v199
	s_nop 0
	v_cndmask_b32_e32 v89, v193, v89, vcc
	v_cmp_lt_u32_e32 vcc, s77, v159
	v_add_u32_e32 v159, 41, v199
	s_nop 0
	v_cndmask_b32_e32 v73, v193, v73, vcc
	v_cmp_lt_u32_e32 vcc, s77, v159
	v_add_u32_e32 v159, 9, v199
	s_nop 0
	v_cndmask_b32_e32 v90, v193, v90, vcc
	v_cmp_lt_u32_e32 vcc, s77, v159
	v_add_u32_e32 v159, 40, v199
	s_nop 0
	v_cndmask_b32_e32 v74, v193, v74, vcc
	v_cmp_lt_u32_e32 vcc, s77, v159
	v_add_u32_e32 v159, 8, v199
	s_nop 0
	v_cndmask_b32_e32 v91, v193, v91, vcc
	v_cmp_lt_u32_e32 vcc, s77, v159
	v_add_u32_e32 v159, 35, v199
	s_nop 0
	v_cndmask_b32_e32 v75, v193, v75, vcc
	v_cmp_lt_u32_e32 vcc, s77, v159
	v_add_u32_e32 v159, 3, v199
	s_nop 0
	v_cndmask_b32_e32 v92, v193, v92, vcc
	v_cmp_lt_u32_e32 vcc, s77, v159
	v_add_u32_e32 v159, 34, v199
	s_nop 0
	v_cndmask_b32_e32 v76, v193, v76, vcc
	v_cmp_lt_u32_e32 vcc, s77, v159
	v_add_u32_e32 v159, 2, v199
	s_nop 0
	v_cndmask_b32_e32 v93, v193, v93, vcc
	v_cmp_lt_u32_e32 vcc, s77, v159
	v_add_u32_e32 v159, 33, v199
	s_nop 0
	v_cndmask_b32_e32 v77, v193, v77, vcc
	v_cmp_lt_u32_e32 vcc, s77, v159
	v_add_u32_e32 v159, 1, v199
	s_nop 0
	v_cndmask_b32_e32 v94, v193, v94, vcc
	v_cmp_lt_u32_e32 vcc, s77, v159
	v_add_u32_e32 v159, 32, v199
	s_nop 0
	v_cndmask_b32_e32 v78, v193, v78, vcc
	v_cmp_lt_u32_e32 vcc, s77, v159
	s_nop 1
	v_cndmask_b32_e32 v95, v193, v95, vcc
	v_cmp_lt_u32_e32 vcc, s77, v199
	s_nop 1
	v_cndmask_b32_e32 v79, v193, v79, vcc

.LBB0_1240:
	v_cndmask_b32_e64 v204, v129, v158, s[10:11]
	v_mul_f32_e32 v130, 0xbe0293ee, v204
	v_mov_b32_e32 v129, v130
	v_fmamk_f32 v80, v80, 0x3e0293ee, v130
	v_fmamk_f32 v81, v81, 0x3e0293ee, v130
	v_fmamk_f32 v82, v82, 0x3e0293ee, v130
	v_fmamk_f32 v83, v83, 0x3e0293ee, v130
	v_fmamk_f32 v84, v84, 0x3e0293ee, v130
	v_fmamk_f32 v85, v85, 0x3e0293ee, v130
	v_fmamk_f32 v86, v86, 0x3e0293ee, v130
	v_fmamk_f32 v87, v87, 0x3e0293ee, v130
	v_fmamk_f32 v88, v88, 0x3e0293ee, v130
	v_fmamk_f32 v89, v89, 0x3e0293ee, v130
	v_fmamk_f32 v90, v90, 0x3e0293ee, v130
	v_fmamk_f32 v91, v91, 0x3e0293ee, v130
	v_fmamk_f32 v92, v92, 0x3e0293ee, v130
	v_fmamk_f32 v93, v93, 0x3e0293ee, v130
	v_fmamk_f32 v94, v94, 0x3e0293ee, v130
	v_fmac_f32_e32 v129, 0x3e0293ee, v95
	v_exp_f32_e32 v219, v80
	v_exp_f32_e32 v221, v81
	v_exp_f32_e32 v217, v82
	v_exp_f32_e32 v220, v83
	v_exp_f32_e32 v216, v84
	v_exp_f32_e32 v218, v85
	v_exp_f32_e32 v214, v86
	v_exp_f32_e32 v215, v87
	v_exp_f32_e32 v211, v88
	v_exp_f32_e32 v213, v89
	v_exp_f32_e32 v210, v90
	v_exp_f32_e32 v212, v91
	v_exp_f32_e32 v207, v92
	v_exp_f32_e32 v209, v93
	v_exp_f32_e32 v205, v94
	v_exp_f32_e32 v208, v129
	v_pk_fma_f32 v[172:173], v[64:65], s[30:31], v[130:131] op_sel_hi:[1,0,0]
	v_add_f32_e32 v64, v201, v202
	v_fmac_f32_e32 v64, v198, v155
	v_add_f32_e32 v155, v232, v233
	s_addk_i32 s87, 0x80
	s_add_i32 s8, s88, 2
	s_add_i32 s0, s88, 1
	v_pk_fma_f32 v[158:159], v[78:79], s[30:31], v[130:131] op_sel_hi:[1,0,0]
	v_pk_fma_f32 v[160:161], v[76:77], s[30:31], v[130:131] op_sel_hi:[1,0,0]
	v_pk_fma_f32 v[162:163], v[74:75], s[30:31], v[130:131] op_sel_hi:[1,0,0]
	v_pk_fma_f32 v[164:165], v[72:73], s[30:31], v[130:131] op_sel_hi:[1,0,0]
	v_pk_fma_f32 v[166:167], v[70:71], s[30:31], v[130:131] op_sel_hi:[1,0,0]
	v_pk_fma_f32 v[168:169], v[68:69], s[30:31], v[130:131] op_sel_hi:[1,0,0]
	v_pk_fma_f32 v[170:171], v[66:67], s[30:31], v[130:131] op_sel_hi:[1,0,0]
	v_fmac_f32_e32 v155, v64, v203
	s_cmp_ge_i32 s0, s23
	v_add_u32_e32 v199, 0xffffff80, v199
	s_waitcnt lgkmcnt(0)
	s_barrier
	s_cbranch_scc1 .LBB0_1245
	s_mov_b32 s88, s8
	v_mov_b32_e32 v198, v128
	s_branch .LBB0_1213
